# merge epilogue: all 16 gate loads up front (was load+vmcnt(0) per store); phase-3 uq/K/V epilogues: per-row rstd/cos/sin loads hoisted
# baseline (speedup 1.0000x reference)
.LBB0_150:
	v_mov_b32_e32 v64, v203
	s_mov_b64 s[2:3], -1
	v_and_or_b32 v132, v64, 15, s67
	v_lshrrev_b32_e32 v64, 1, v64
	v_and_or_b32 v64, v64, 24, s62
	v_or_b32_e32 v66, s66, v64
	v_ashrrev_i32_e32 v133, 31, v132
	v_lshlrev_b64 v[140:141], 11, v[132:133]
	v_ashrrev_i32_e32 v67, 31, v66
	v_lshl_add_u64 v[134:135], s[46:47], 0, v[140:141]
	v_lshlrev_b64 v[66:67], 1, v[66:67]
	v_lshl_add_u64 v[134:135], v[134:135], 0, v[66:67]
	v_mov_b32_e32 v222, v134
	v_mov_b32_e32 v223, v135
	v_mov_b32_e32 v144, v222
	v_mov_b32_e32 v145, v223
	global_load_dwordx4 v[148:151], v[144:145], off offset:256 nt
	global_load_dwordx4 v[144:147], v[144:145], off nt
	s_mov_b64 s[98:99], 0x8000
	v_lshl_add_u64 v[152:153], v[222:223], 0, s[98:99]
	global_load_dwordx4 v[156:159], v[152:153], off offset:256 nt
	global_load_dwordx4 v[152:155], v[152:153], off nt
	s_mov_b64 s[98:99], 0x10000
	v_lshl_add_u64 v[160:161], v[222:223], 0, s[98:99]
	global_load_dwordx4 v[164:167], v[160:161], off offset:256 nt
	global_load_dwordx4 v[160:163], v[160:161], off nt
	s_mov_b64 s[98:99], 0x18000
	v_lshl_add_u64 v[168:169], v[222:223], 0, s[98:99]
	global_load_dwordx4 v[172:175], v[168:169], off offset:256 nt
	global_load_dwordx4 v[168:171], v[168:169], off nt
	s_mov_b64 s[98:99], 0x40000
	v_lshl_add_u64 v[176:177], v[222:223], 0, s[98:99]
	global_load_dwordx4 v[180:183], v[176:177], off offset:256 nt
	global_load_dwordx4 v[176:179], v[176:177], off nt
	s_mov_b64 s[98:99], 0x48000
	v_lshl_add_u64 v[184:185], v[222:223], 0, s[98:99]
	global_load_dwordx4 v[190:193], v[184:185], off offset:256 nt
	global_load_dwordx4 v[184:187], v[184:185], off nt
	s_mov_b64 s[98:99], 0x50000
	v_lshl_add_u64 v[194:195], v[222:223], 0, s[98:99]
	global_load_dwordx4 v[198:201], v[194:195], off offset:256 nt
	global_load_dwordx4 v[194:197], v[194:195], off nt
	s_mov_b64 s[98:99], 0x58000
	v_lshl_add_u64 v[214:215], v[222:223], 0, s[98:99]
	global_load_dwordx4 v[218:221], v[214:215], off offset:256 nt
	global_load_dwordx4 v[214:217], v[214:215], off nt
	s_andn2_b64 vcc, exec, s[82:83]
	v_readlane_b32 s71, v254, 49
	s_waitcnt vmcnt(14)
	v_lshlrev_b32_e32 v64, 16, v144
	v_max_f32_e32 v64, v64, v64
	v_med3_f32 v64, v64, s72, v204
	v_mul_f32_e32 v64, 0xbfb8aa3b, v64
	v_exp_f32_e32 v64, v64
	s_nop 0
	v_add_f32_e32 v64, 1.0, v64
	v_rcp_f32_e32 v142, v64
	v_and_b32_e32 v64, 0xffff0000, v144
	v_max_f32_e32 v64, v64, v64
	v_med3_f32 v64, v64, s72, v204
	v_mul_f32_e32 v64, 0xbfb8aa3b, v64
	v_exp_f32_e32 v64, v64
	s_nop 0
	v_add_f32_e32 v64, 1.0, v64
	v_rcp_f32_e32 v143, v64
	v_lshlrev_b32_e32 v64, 16, v145
	v_max_f32_e32 v64, v64, v64
	v_med3_f32 v64, v64, s72, v204
	v_mul_f32_e32 v64, 0xbfb8aa3b, v64
	v_exp_f32_e32 v64, v64
	v_pk_mul_f32 v[128:129], v[128:129], v[142:143]
	v_add_f32_e32 v64, 1.0, v64
	v_rcp_f32_e32 v136, v64
	v_and_b32_e32 v64, 0xffff0000, v145
	v_max_f32_e32 v64, v64, v64
	v_med3_f32 v64, v64, s72, v204
	v_mul_f32_e32 v64, 0xbfb8aa3b, v64
	v_exp_f32_e32 v64, v64
	v_cvt_pk_bf16_f32 v128, v128, v129
	v_add_f32_e32 v64, 1.0, v64
	v_rcp_f32_e32 v137, v64
	v_lshlrev_b32_e32 v64, 16, v146
	v_max_f32_e32 v64, v64, v64
	v_med3_f32 v64, v64, s72, v204
	v_mul_f32_e32 v64, 0xbfb8aa3b, v64
	v_exp_f32_e32 v64, v64
	v_pk_mul_f32 v[130:131], v[130:131], v[136:137]
	v_add_f32_e32 v64, 1.0, v64
	v_cvt_pk_bf16_f32 v129, v130, v131
	v_rcp_f32_e32 v130, v64
	v_and_b32_e32 v64, 0xffff0000, v146
	v_max_f32_e32 v64, v64, v64
	v_med3_f32 v64, v64, s72, v204
	v_mul_f32_e32 v64, 0xbfb8aa3b, v64
	v_exp_f32_e32 v64, v64
	s_nop 0
	v_add_f32_e32 v64, 1.0, v64
	v_rcp_f32_e32 v131, v64
	v_lshlrev_b32_e32 v64, 16, v147
	v_max_f32_e32 v64, v64, v64
	v_med3_f32 v64, v64, s72, v204
	v_mul_f32_e32 v64, 0xbfb8aa3b, v64
	v_exp_f32_e32 v64, v64
	v_pk_mul_f32 v[124:125], v[124:125], v[130:131]
	v_add_f32_e32 v64, 1.0, v64
	v_cvt_pk_bf16_f32 v130, v124, v125
	v_rcp_f32_e32 v124, v64
	v_and_b32_e32 v64, 0xffff0000, v147
	v_max_f32_e32 v64, v64, v64
	v_med3_f32 v64, v64, s72, v204
	v_mul_f32_e32 v64, 0xbfb8aa3b, v64
	v_exp_f32_e32 v64, v64
	s_nop 0
	v_add_f32_e32 v64, 1.0, v64
	v_rcp_f32_e32 v125, v64
	s_nop 0
	v_pk_mul_f32 v[124:125], v[126:127], v[124:125]
	s_nop 0
	v_cvt_pk_bf16_f32 v131, v124, v125
	v_lshl_add_u64 v[124:125], s[56:57], 0, v[140:141]
	v_lshl_add_u64 v[124:125], v[124:125], 0, v[66:67]
	global_store_dwordx4 v[124:125], v[128:131], off
	s_nop 1
	s_waitcnt vmcnt(16)
	v_lshlrev_b32_e32 v64, 16, v148
	v_max_f32_e32 v64, v64, v64
	v_med3_f32 v64, v64, s72, v204
	v_mul_f32_e32 v64, 0xbfb8aa3b, v64
	v_exp_f32_e32 v64, v64
	s_nop 0
	v_add_f32_e32 v64, 1.0, v64
	v_rcp_f32_e32 v130, v64
	v_and_b32_e32 v64, 0xffff0000, v148
	v_max_f32_e32 v64, v64, v64
	v_med3_f32 v64, v64, s72, v204
	v_mul_f32_e32 v64, 0xbfb8aa3b, v64
	v_exp_f32_e32 v64, v64
	s_nop 0
	v_add_f32_e32 v64, 1.0, v64
	v_rcp_f32_e32 v131, v64
	v_lshlrev_b32_e32 v64, 16, v149
	v_max_f32_e32 v64, v64, v64
	v_med3_f32 v64, v64, s72, v204
	v_mul_f32_e32 v64, 0xbfb8aa3b, v64
	v_exp_f32_e32 v64, v64
	v_pk_mul_f32 v[120:121], v[120:121], v[130:131]
	v_add_f32_e32 v64, 1.0, v64
	v_rcp_f32_e32 v126, v64
	v_and_b32_e32 v64, 0xffff0000, v149
	v_max_f32_e32 v64, v64, v64
	v_med3_f32 v64, v64, s72, v204
	v_mul_f32_e32 v64, 0xbfb8aa3b, v64
	v_exp_f32_e32 v64, v64
	v_cvt_pk_bf16_f32 v120, v120, v121
	v_add_f32_e32 v64, 1.0, v64
	v_rcp_f32_e32 v127, v64
	v_lshlrev_b32_e32 v64, 16, v150
	v_max_f32_e32 v64, v64, v64
	v_med3_f32 v64, v64, s72, v204
	v_mul_f32_e32 v64, 0xbfb8aa3b, v64
	v_exp_f32_e32 v64, v64
	v_pk_mul_f32 v[122:123], v[122:123], v[126:127]
	v_add_f32_e32 v64, 1.0, v64
	v_cvt_pk_bf16_f32 v121, v122, v123
	v_rcp_f32_e32 v122, v64
	v_and_b32_e32 v64, 0xffff0000, v150
	v_max_f32_e32 v64, v64, v64
	v_med3_f32 v64, v64, s72, v204
	v_mul_f32_e32 v64, 0xbfb8aa3b, v64
	v_exp_f32_e32 v64, v64
	s_nop 0
	v_add_f32_e32 v64, 1.0, v64
	v_rcp_f32_e32 v123, v64
	v_lshlrev_b32_e32 v64, 16, v151
	v_max_f32_e32 v64, v64, v64
	v_med3_f32 v64, v64, s72, v204
	v_mul_f32_e32 v64, 0xbfb8aa3b, v64
	v_exp_f32_e32 v64, v64
	v_pk_mul_f32 v[116:117], v[116:117], v[122:123]
	v_add_f32_e32 v64, 1.0, v64
	v_cvt_pk_bf16_f32 v122, v116, v117
	v_rcp_f32_e32 v116, v64
	v_and_b32_e32 v64, 0xffff0000, v151
	v_max_f32_e32 v64, v64, v64
	v_med3_f32 v64, v64, s72, v204
	v_mul_f32_e32 v64, 0xbfb8aa3b, v64
	v_exp_f32_e32 v64, v64
	s_nop 0
	v_add_f32_e32 v64, 1.0, v64
	v_rcp_f32_e32 v117, v64
	s_nop 0
	v_pk_mul_f32 v[116:117], v[118:119], v[116:117]
	s_nop 0
	v_cvt_pk_bf16_f32 v123, v116, v117
	v_or_b32_e32 v116, 16, v132
	v_ashrrev_i32_e32 v117, 31, v116
	global_store_dwordx4 v[124:125], v[120:123], off offset:256
	s_nop 1
	v_lshlrev_b64 v[122:123], 11, v[116:117]
	v_lshl_add_u64 v[116:117], s[46:47], 0, v[122:123]
	v_lshl_add_u64 v[116:117], v[116:117], 0, v[66:67]
	s_nop 1
	s_waitcnt vmcnt(14)
	v_lshlrev_b32_e32 v64, 16, v152
	v_max_f32_e32 v64, v64, v64
	v_med3_f32 v64, v64, s72, v204
	v_mul_f32_e32 v64, 0xbfb8aa3b, v64
	v_exp_f32_e32 v64, v64
	s_nop 0
	v_add_f32_e32 v64, 1.0, v64
	v_rcp_f32_e32 v124, v64
	v_and_b32_e32 v64, 0xffff0000, v152
	v_max_f32_e32 v64, v64, v64
	v_med3_f32 v64, v64, s72, v204
	v_mul_f32_e32 v64, 0xbfb8aa3b, v64
	v_exp_f32_e32 v64, v64
	s_nop 0
	v_add_f32_e32 v64, 1.0, v64
	v_rcp_f32_e32 v125, v64
	v_lshlrev_b32_e32 v64, 16, v153
	v_max_f32_e32 v64, v64, v64
	v_med3_f32 v64, v64, s72, v204
	v_mul_f32_e32 v64, 0xbfb8aa3b, v64
	v_exp_f32_e32 v64, v64
	v_pk_mul_f32 v[112:113], v[112:113], v[124:125]
	v_add_f32_e32 v64, 1.0, v64
	v_rcp_f32_e32 v118, v64
	v_and_b32_e32 v64, 0xffff0000, v153
	v_max_f32_e32 v64, v64, v64
	v_med3_f32 v64, v64, s72, v204
	v_mul_f32_e32 v64, 0xbfb8aa3b, v64
	v_exp_f32_e32 v64, v64
	v_cvt_pk_bf16_f32 v112, v112, v113
	v_add_f32_e32 v64, 1.0, v64
	v_rcp_f32_e32 v119, v64
	v_lshlrev_b32_e32 v64, 16, v154
	v_max_f32_e32 v64, v64, v64
	v_med3_f32 v64, v64, s72, v204
	v_mul_f32_e32 v64, 0xbfb8aa3b, v64
	v_exp_f32_e32 v64, v64
	v_pk_mul_f32 v[114:115], v[114:115], v[118:119]
	v_add_f32_e32 v64, 1.0, v64
	v_cvt_pk_bf16_f32 v113, v114, v115
	v_rcp_f32_e32 v114, v64
	v_and_b32_e32 v64, 0xffff0000, v154
	v_max_f32_e32 v64, v64, v64
	v_med3_f32 v64, v64, s72, v204
	v_mul_f32_e32 v64, 0xbfb8aa3b, v64
	v_exp_f32_e32 v64, v64
	s_nop 0
	v_add_f32_e32 v64, 1.0, v64
	v_rcp_f32_e32 v115, v64
	v_lshlrev_b32_e32 v64, 16, v155
	v_max_f32_e32 v64, v64, v64
	v_med3_f32 v64, v64, s72, v204
	v_mul_f32_e32 v64, 0xbfb8aa3b, v64
	v_exp_f32_e32 v64, v64
	v_pk_mul_f32 v[108:109], v[108:109], v[114:115]
	v_add_f32_e32 v64, 1.0, v64
	v_cvt_pk_bf16_f32 v114, v108, v109
	v_rcp_f32_e32 v108, v64
	v_and_b32_e32 v64, 0xffff0000, v155
	v_max_f32_e32 v64, v64, v64
	v_med3_f32 v64, v64, s72, v204
	v_mul_f32_e32 v64, 0xbfb8aa3b, v64
	v_exp_f32_e32 v64, v64
	s_nop 0
	v_add_f32_e32 v64, 1.0, v64
	v_rcp_f32_e32 v109, v64
	s_nop 0
	v_pk_mul_f32 v[108:109], v[110:111], v[108:109]
	s_nop 0
	v_cvt_pk_bf16_f32 v115, v108, v109
	v_lshl_add_u64 v[108:109], s[56:57], 0, v[122:123]
	v_lshl_add_u64 v[108:109], v[108:109], 0, v[66:67]
	global_store_dwordx4 v[108:109], v[112:115], off
	s_nop 1
	s_waitcnt vmcnt(16)
	v_lshlrev_b32_e32 v64, 16, v156
	v_max_f32_e32 v64, v64, v64
	v_med3_f32 v64, v64, s72, v204
	v_mul_f32_e32 v64, 0xbfb8aa3b, v64
	v_exp_f32_e32 v64, v64
	s_nop 0
	v_add_f32_e32 v64, 1.0, v64
	v_rcp_f32_e32 v114, v64
	v_and_b32_e32 v64, 0xffff0000, v156
	v_max_f32_e32 v64, v64, v64
	v_med3_f32 v64, v64, s72, v204
	v_mul_f32_e32 v64, 0xbfb8aa3b, v64
	v_exp_f32_e32 v64, v64
	s_nop 0
	v_add_f32_e32 v64, 1.0, v64
	v_rcp_f32_e32 v115, v64
	v_lshlrev_b32_e32 v64, 16, v157
	v_max_f32_e32 v64, v64, v64
	v_med3_f32 v64, v64, s72, v204
	v_mul_f32_e32 v64, 0xbfb8aa3b, v64
	v_exp_f32_e32 v64, v64
	v_pk_mul_f32 v[104:105], v[104:105], v[114:115]
	v_add_f32_e32 v64, 1.0, v64
	v_rcp_f32_e32 v110, v64
	v_and_b32_e32 v64, 0xffff0000, v157
	v_max_f32_e32 v64, v64, v64
	v_med3_f32 v64, v64, s72, v204
	v_mul_f32_e32 v64, 0xbfb8aa3b, v64
	v_exp_f32_e32 v64, v64
	v_cvt_pk_bf16_f32 v104, v104, v105
	v_add_f32_e32 v64, 1.0, v64
	v_rcp_f32_e32 v111, v64
	v_lshlrev_b32_e32 v64, 16, v158
	v_max_f32_e32 v64, v64, v64
	v_med3_f32 v64, v64, s72, v204
	v_mul_f32_e32 v64, 0xbfb8aa3b, v64
	v_exp_f32_e32 v64, v64
	v_pk_mul_f32 v[106:107], v[106:107], v[110:111]
	v_add_f32_e32 v64, 1.0, v64
	v_cvt_pk_bf16_f32 v105, v106, v107
	v_rcp_f32_e32 v106, v64
	v_and_b32_e32 v64, 0xffff0000, v158
	v_max_f32_e32 v64, v64, v64
	v_med3_f32 v64, v64, s72, v204
	v_mul_f32_e32 v64, 0xbfb8aa3b, v64
	v_exp_f32_e32 v64, v64
	s_nop 0
	v_add_f32_e32 v64, 1.0, v64
	v_rcp_f32_e32 v107, v64
	v_lshlrev_b32_e32 v64, 16, v159
	v_max_f32_e32 v64, v64, v64
	v_med3_f32 v64, v64, s72, v204
	v_mul_f32_e32 v64, 0xbfb8aa3b, v64
	v_exp_f32_e32 v64, v64
	v_pk_mul_f32 v[100:101], v[100:101], v[106:107]
	v_add_f32_e32 v64, 1.0, v64
	v_cvt_pk_bf16_f32 v106, v100, v101
	v_rcp_f32_e32 v100, v64
	v_and_b32_e32 v64, 0xffff0000, v159
	v_max_f32_e32 v64, v64, v64
	v_med3_f32 v64, v64, s72, v204
	v_mul_f32_e32 v64, 0xbfb8aa3b, v64
	v_exp_f32_e32 v64, v64
	s_nop 0
	v_add_f32_e32 v64, 1.0, v64
	v_rcp_f32_e32 v101, v64
	s_nop 0
	v_pk_mul_f32 v[100:101], v[102:103], v[100:101]
	s_nop 0
	v_cvt_pk_bf16_f32 v107, v100, v101
	v_or_b32_e32 v100, 32, v132
	v_ashrrev_i32_e32 v101, 31, v100
	global_store_dwordx4 v[108:109], v[104:107], off offset:256
	s_nop 1
	v_lshlrev_b64 v[106:107], 11, v[100:101]
	v_lshl_add_u64 v[100:101], s[46:47], 0, v[106:107]
	v_lshl_add_u64 v[100:101], v[100:101], 0, v[66:67]
	s_nop 1
	s_waitcnt vmcnt(14)
	v_lshlrev_b32_e32 v64, 16, v160
	v_max_f32_e32 v64, v64, v64
	v_med3_f32 v64, v64, s72, v204
	v_mul_f32_e32 v64, 0xbfb8aa3b, v64
	v_exp_f32_e32 v64, v64
	s_nop 0
	v_add_f32_e32 v64, 1.0, v64
	v_rcp_f32_e32 v108, v64
	v_and_b32_e32 v64, 0xffff0000, v160
	v_max_f32_e32 v64, v64, v64
	v_med3_f32 v64, v64, s72, v204
	v_mul_f32_e32 v64, 0xbfb8aa3b, v64
	v_exp_f32_e32 v64, v64
	s_nop 0
	v_add_f32_e32 v64, 1.0, v64
	v_rcp_f32_e32 v109, v64
	v_lshlrev_b32_e32 v64, 16, v161
	v_max_f32_e32 v64, v64, v64
	v_med3_f32 v64, v64, s72, v204
	v_mul_f32_e32 v64, 0xbfb8aa3b, v64
	v_exp_f32_e32 v64, v64
	v_pk_mul_f32 v[96:97], v[96:97], v[108:109]
	v_add_f32_e32 v64, 1.0, v64
	v_rcp_f32_e32 v102, v64
	v_and_b32_e32 v64, 0xffff0000, v161
	v_max_f32_e32 v64, v64, v64
	v_med3_f32 v64, v64, s72, v204
	v_mul_f32_e32 v64, 0xbfb8aa3b, v64
	v_exp_f32_e32 v64, v64
	v_cvt_pk_bf16_f32 v96, v96, v97
	v_add_f32_e32 v64, 1.0, v64
	v_rcp_f32_e32 v103, v64
	v_lshlrev_b32_e32 v64, 16, v162
	v_max_f32_e32 v64, v64, v64
	v_med3_f32 v64, v64, s72, v204
	v_mul_f32_e32 v64, 0xbfb8aa3b, v64
	v_exp_f32_e32 v64, v64
	v_pk_mul_f32 v[98:99], v[98:99], v[102:103]
	v_add_f32_e32 v64, 1.0, v64
	v_cvt_pk_bf16_f32 v97, v98, v99
	v_rcp_f32_e32 v98, v64
	v_and_b32_e32 v64, 0xffff0000, v162
	v_max_f32_e32 v64, v64, v64
	v_med3_f32 v64, v64, s72, v204
	v_mul_f32_e32 v64, 0xbfb8aa3b, v64
	v_exp_f32_e32 v64, v64
	s_nop 0
	v_add_f32_e32 v64, 1.0, v64
	v_rcp_f32_e32 v99, v64
	v_lshlrev_b32_e32 v64, 16, v163
	v_max_f32_e32 v64, v64, v64
	v_med3_f32 v64, v64, s72, v204
	v_mul_f32_e32 v64, 0xbfb8aa3b, v64
	v_exp_f32_e32 v64, v64
	v_pk_mul_f32 v[92:93], v[92:93], v[98:99]
	v_add_f32_e32 v64, 1.0, v64
	v_cvt_pk_bf16_f32 v98, v92, v93
	v_rcp_f32_e32 v92, v64
	v_and_b32_e32 v64, 0xffff0000, v163
	v_max_f32_e32 v64, v64, v64
	v_med3_f32 v64, v64, s72, v204
	v_mul_f32_e32 v64, 0xbfb8aa3b, v64
	v_exp_f32_e32 v64, v64
	s_nop 0
	v_add_f32_e32 v64, 1.0, v64
	v_rcp_f32_e32 v93, v64
	s_nop 0
	v_pk_mul_f32 v[92:93], v[94:95], v[92:93]
	s_nop 0
	v_cvt_pk_bf16_f32 v99, v92, v93
	v_lshl_add_u64 v[92:93], s[56:57], 0, v[106:107]
	v_lshl_add_u64 v[92:93], v[92:93], 0, v[66:67]
	global_store_dwordx4 v[92:93], v[96:99], off
	s_nop 1
	s_waitcnt vmcnt(16)
	v_lshlrev_b32_e32 v64, 16, v164
	v_max_f32_e32 v64, v64, v64
	v_med3_f32 v64, v64, s72, v204
	v_mul_f32_e32 v64, 0xbfb8aa3b, v64
	v_exp_f32_e32 v64, v64
	s_nop 0
	v_add_f32_e32 v64, 1.0, v64
	v_rcp_f32_e32 v98, v64
	v_and_b32_e32 v64, 0xffff0000, v164
	v_max_f32_e32 v64, v64, v64
	v_med3_f32 v64, v64, s72, v204
	v_mul_f32_e32 v64, 0xbfb8aa3b, v64
	v_exp_f32_e32 v64, v64
	s_nop 0
	v_add_f32_e32 v64, 1.0, v64
	v_rcp_f32_e32 v99, v64
	v_lshlrev_b32_e32 v64, 16, v165
	v_max_f32_e32 v64, v64, v64
	v_med3_f32 v64, v64, s72, v204
	v_mul_f32_e32 v64, 0xbfb8aa3b, v64
	v_exp_f32_e32 v64, v64
	v_pk_mul_f32 v[88:89], v[88:89], v[98:99]
	v_add_f32_e32 v64, 1.0, v64
	v_rcp_f32_e32 v94, v64
	v_and_b32_e32 v64, 0xffff0000, v165
	v_max_f32_e32 v64, v64, v64
	v_med3_f32 v64, v64, s72, v204
	v_mul_f32_e32 v64, 0xbfb8aa3b, v64
	v_exp_f32_e32 v64, v64
	v_cvt_pk_bf16_f32 v88, v88, v89
	v_add_f32_e32 v64, 1.0, v64
	v_rcp_f32_e32 v95, v64
	v_lshlrev_b32_e32 v64, 16, v166
	v_max_f32_e32 v64, v64, v64
	v_med3_f32 v64, v64, s72, v204
	v_mul_f32_e32 v64, 0xbfb8aa3b, v64
	v_exp_f32_e32 v64, v64
	v_pk_mul_f32 v[90:91], v[90:91], v[94:95]
	v_add_f32_e32 v64, 1.0, v64
	v_cvt_pk_bf16_f32 v89, v90, v91
	v_rcp_f32_e32 v90, v64
	v_and_b32_e32 v64, 0xffff0000, v166
	v_max_f32_e32 v64, v64, v64
	v_med3_f32 v64, v64, s72, v204
	v_mul_f32_e32 v64, 0xbfb8aa3b, v64
	v_exp_f32_e32 v64, v64
	s_nop 0
	v_add_f32_e32 v64, 1.0, v64
	v_rcp_f32_e32 v91, v64
	v_lshlrev_b32_e32 v64, 16, v167
	v_max_f32_e32 v64, v64, v64
	v_med3_f32 v64, v64, s72, v204
	v_mul_f32_e32 v64, 0xbfb8aa3b, v64
	v_exp_f32_e32 v64, v64
	v_pk_mul_f32 v[84:85], v[84:85], v[90:91]
	v_add_f32_e32 v64, 1.0, v64
	v_cvt_pk_bf16_f32 v90, v84, v85
	v_rcp_f32_e32 v84, v64
	v_and_b32_e32 v64, 0xffff0000, v167
	v_max_f32_e32 v64, v64, v64
	v_med3_f32 v64, v64, s72, v204
	v_mul_f32_e32 v64, 0xbfb8aa3b, v64
	v_exp_f32_e32 v64, v64
	s_nop 0
	v_add_f32_e32 v64, 1.0, v64
	v_rcp_f32_e32 v85, v64
	s_nop 0
	v_pk_mul_f32 v[84:85], v[86:87], v[84:85]
	s_nop 0
	v_cvt_pk_bf16_f32 v91, v84, v85
	v_or_b32_e32 v84, 48, v132
	v_ashrrev_i32_e32 v85, 31, v84
	global_store_dwordx4 v[92:93], v[88:91], off offset:256
	s_nop 1
	v_lshlrev_b64 v[90:91], 11, v[84:85]
	v_lshl_add_u64 v[84:85], s[46:47], 0, v[90:91]
	v_lshl_add_u64 v[84:85], v[84:85], 0, v[66:67]
	s_nop 1
	s_waitcnt vmcnt(14)
	v_lshlrev_b32_e32 v64, 16, v168
	v_max_f32_e32 v64, v64, v64
	v_med3_f32 v64, v64, s72, v204
	v_mul_f32_e32 v64, 0xbfb8aa3b, v64
	v_exp_f32_e32 v64, v64
	s_nop 0
	v_add_f32_e32 v64, 1.0, v64
	v_rcp_f32_e32 v92, v64
	v_and_b32_e32 v64, 0xffff0000, v168
	v_max_f32_e32 v64, v64, v64
	v_med3_f32 v64, v64, s72, v204
	v_mul_f32_e32 v64, 0xbfb8aa3b, v64
	v_exp_f32_e32 v64, v64
	s_nop 0
	v_add_f32_e32 v64, 1.0, v64
	v_rcp_f32_e32 v93, v64
	v_lshlrev_b32_e32 v64, 16, v169
	v_max_f32_e32 v64, v64, v64
	v_med3_f32 v64, v64, s72, v204
	v_mul_f32_e32 v64, 0xbfb8aa3b, v64
	v_exp_f32_e32 v64, v64
	v_pk_mul_f32 v[80:81], v[80:81], v[92:93]
	v_add_f32_e32 v64, 1.0, v64
	v_rcp_f32_e32 v86, v64
	v_and_b32_e32 v64, 0xffff0000, v169
	v_max_f32_e32 v64, v64, v64
	v_med3_f32 v64, v64, s72, v204
	v_mul_f32_e32 v64, 0xbfb8aa3b, v64
	v_exp_f32_e32 v64, v64
	v_cvt_pk_bf16_f32 v80, v80, v81
	v_add_f32_e32 v64, 1.0, v64
	v_rcp_f32_e32 v87, v64
	v_lshlrev_b32_e32 v64, 16, v170
	v_max_f32_e32 v64, v64, v64
	v_med3_f32 v64, v64, s72, v204
	v_mul_f32_e32 v64, 0xbfb8aa3b, v64
	v_exp_f32_e32 v64, v64
	v_pk_mul_f32 v[82:83], v[82:83], v[86:87]
	v_add_f32_e32 v64, 1.0, v64
	v_cvt_pk_bf16_f32 v81, v82, v83
	v_rcp_f32_e32 v82, v64
	v_and_b32_e32 v64, 0xffff0000, v170
	v_max_f32_e32 v64, v64, v64
	v_med3_f32 v64, v64, s72, v204
	v_mul_f32_e32 v64, 0xbfb8aa3b, v64
	v_exp_f32_e32 v64, v64
	s_nop 0
	v_add_f32_e32 v64, 1.0, v64
	v_rcp_f32_e32 v83, v64
	v_lshlrev_b32_e32 v64, 16, v171
	v_max_f32_e32 v64, v64, v64
	v_med3_f32 v64, v64, s72, v204
	v_mul_f32_e32 v64, 0xbfb8aa3b, v64
	v_exp_f32_e32 v64, v64
	v_pk_mul_f32 v[76:77], v[76:77], v[82:83]
	v_add_f32_e32 v64, 1.0, v64
	v_cvt_pk_bf16_f32 v82, v76, v77
	v_rcp_f32_e32 v76, v64
	v_and_b32_e32 v64, 0xffff0000, v171
	v_max_f32_e32 v64, v64, v64
	v_med3_f32 v64, v64, s72, v204
	v_mul_f32_e32 v64, 0xbfb8aa3b, v64
	v_exp_f32_e32 v64, v64
	s_nop 0
	v_add_f32_e32 v64, 1.0, v64
	v_rcp_f32_e32 v77, v64
	s_nop 0
	v_pk_mul_f32 v[76:77], v[78:79], v[76:77]
	s_nop 0
	v_cvt_pk_bf16_f32 v83, v76, v77
	v_lshl_add_u64 v[76:77], s[56:57], 0, v[90:91]
	v_lshl_add_u64 v[76:77], v[76:77], 0, v[66:67]
	global_store_dwordx4 v[76:77], v[80:83], off
	s_nop 1
	s_waitcnt vmcnt(16)
	v_lshlrev_b32_e32 v64, 16, v172
	v_max_f32_e32 v64, v64, v64
	v_med3_f32 v64, v64, s72, v204
	v_mul_f32_e32 v64, 0xbfb8aa3b, v64
	v_exp_f32_e32 v64, v64
	s_nop 0
	v_add_f32_e32 v64, 1.0, v64
	v_rcp_f32_e32 v82, v64
	v_and_b32_e32 v64, 0xffff0000, v172
	v_max_f32_e32 v64, v64, v64
	v_med3_f32 v64, v64, s72, v204
	v_mul_f32_e32 v64, 0xbfb8aa3b, v64
	v_exp_f32_e32 v64, v64
	s_nop 0
	v_add_f32_e32 v64, 1.0, v64
	v_rcp_f32_e32 v83, v64
	v_lshlrev_b32_e32 v64, 16, v173
	v_max_f32_e32 v64, v64, v64
	v_med3_f32 v64, v64, s72, v204
	v_mul_f32_e32 v64, 0xbfb8aa3b, v64
	v_exp_f32_e32 v64, v64
	v_pk_mul_f32 v[72:73], v[72:73], v[82:83]
	v_add_f32_e32 v64, 1.0, v64
	v_rcp_f32_e32 v78, v64
	v_and_b32_e32 v64, 0xffff0000, v173
	v_max_f32_e32 v64, v64, v64
	v_med3_f32 v64, v64, s72, v204
	v_mul_f32_e32 v64, 0xbfb8aa3b, v64
	v_exp_f32_e32 v64, v64
	v_cvt_pk_bf16_f32 v72, v72, v73
	v_add_f32_e32 v64, 1.0, v64
	v_rcp_f32_e32 v79, v64
	v_lshlrev_b32_e32 v64, 16, v174
	v_max_f32_e32 v64, v64, v64
	v_med3_f32 v64, v64, s72, v204
	v_mul_f32_e32 v64, 0xbfb8aa3b, v64
	v_exp_f32_e32 v64, v64
	v_pk_mul_f32 v[74:75], v[74:75], v[78:79]
	v_add_f32_e32 v64, 1.0, v64
	v_cvt_pk_bf16_f32 v73, v74, v75
	v_rcp_f32_e32 v74, v64
	v_and_b32_e32 v64, 0xffff0000, v174
	v_max_f32_e32 v64, v64, v64
	v_med3_f32 v64, v64, s72, v204
	v_mul_f32_e32 v64, 0xbfb8aa3b, v64
	v_exp_f32_e32 v64, v64
	s_nop 0
	v_add_f32_e32 v64, 1.0, v64
	v_rcp_f32_e32 v75, v64
	v_lshlrev_b32_e32 v64, 16, v175
	v_max_f32_e32 v64, v64, v64
	v_med3_f32 v64, v64, s72, v204
	v_mul_f32_e32 v64, 0xbfb8aa3b, v64
	v_exp_f32_e32 v64, v64
	v_pk_mul_f32 v[68:69], v[68:69], v[74:75]
	v_add_f32_e32 v64, 1.0, v64
	v_cvt_pk_bf16_f32 v74, v68, v69
	v_rcp_f32_e32 v68, v64
	v_and_b32_e32 v64, 0xffff0000, v175
	v_max_f32_e32 v64, v64, v64
	v_med3_f32 v64, v64, s72, v204
	v_mul_f32_e32 v64, 0xbfb8aa3b, v64
	v_exp_f32_e32 v64, v64
	s_nop 0
	v_add_f32_e32 v64, 1.0, v64
	v_rcp_f32_e32 v69, v64
	s_nop 0
	v_pk_mul_f32 v[68:69], v[70:71], v[68:69]
	s_nop 0
	v_cvt_pk_bf16_f32 v75, v68, v69
	v_add_u32_e32 v68, 0x80, v132
	v_ashrrev_i32_e32 v69, 31, v68
	global_store_dwordx4 v[76:77], v[72:75], off offset:256
	s_nop 1
	v_lshlrev_b64 v[74:75], 11, v[68:69]
	v_lshl_add_u64 v[68:69], s[46:47], 0, v[74:75]
	v_lshl_add_u64 v[68:69], v[68:69], 0, v[66:67]
	s_nop 1
	s_waitcnt vmcnt(14)
	v_lshlrev_b32_e32 v64, 16, v176
	v_max_f32_e32 v64, v64, v64
	v_med3_f32 v64, v64, s72, v204
	v_mul_f32_e32 v64, 0xbfb8aa3b, v64
	v_exp_f32_e32 v64, v64
	s_nop 0
	v_add_f32_e32 v64, 1.0, v64
	v_rcp_f32_e32 v76, v64
	v_and_b32_e32 v64, 0xffff0000, v176
	v_max_f32_e32 v64, v64, v64
	v_med3_f32 v64, v64, s72, v204
	v_mul_f32_e32 v64, 0xbfb8aa3b, v64
	v_exp_f32_e32 v64, v64
	s_nop 0
	v_add_f32_e32 v64, 1.0, v64
	v_rcp_f32_e32 v77, v64
	s_nop 0
	v_pk_mul_f32 v[60:61], v[60:61], v[76:77]
	s_nop 0
	v_cvt_pk_bf16_f32 v60, v60, v61
	v_lshlrev_b32_e32 v61, 16, v177
	v_max_f32_e32 v61, v61, v61
	v_med3_f32 v61, v61, s72, v204
	v_mul_f32_e32 v61, 0xbfb8aa3b, v61
	v_exp_f32_e32 v61, v61
	s_nop 0
	v_add_f32_e32 v61, 1.0, v61
	v_rcp_f32_e32 v70, v61
	v_and_b32_e32 v61, 0xffff0000, v177
	v_max_f32_e32 v61, v61, v61
	v_med3_f32 v61, v61, s72, v204
	v_mul_f32_e32 v61, 0xbfb8aa3b, v61
	v_exp_f32_e32 v61, v61
	s_nop 0
	v_add_f32_e32 v61, 1.0, v61
	v_rcp_f32_e32 v71, v61
	s_nop 0
	v_pk_mul_f32 v[62:63], v[62:63], v[70:71]
	s_nop 0
	v_cvt_pk_bf16_f32 v61, v62, v63
	v_lshlrev_b32_e32 v62, 16, v178
	v_and_b32_e32 v63, 0xffff0000, v178
	v_max_f32_e32 v62, v62, v62
	v_max_f32_e32 v63, v63, v63
	v_med3_f32 v62, v62, s72, v204
	v_med3_f32 v63, v63, s72, v204
	v_mul_f32_e32 v62, 0xbfb8aa3b, v62
	v_mul_f32_e32 v63, 0xbfb8aa3b, v63
	v_exp_f32_e32 v62, v62
	v_exp_f32_e32 v63, v63
	v_add_f32_e32 v62, 1.0, v62
	v_add_f32_e32 v63, 1.0, v63
	v_rcp_f32_e32 v62, v62
	v_rcp_f32_e32 v63, v63
	s_nop 0
	v_pk_mul_f32 v[56:57], v[56:57], v[62:63]
	s_nop 0
	v_cvt_pk_bf16_f32 v62, v56, v57
	v_lshlrev_b32_e32 v56, 16, v179
	v_and_b32_e32 v57, 0xffff0000, v179
	v_max_f32_e32 v56, v56, v56
	v_max_f32_e32 v57, v57, v57
	v_med3_f32 v56, v56, s72, v204
	v_med3_f32 v57, v57, s72, v204
	v_mul_f32_e32 v56, 0xbfb8aa3b, v56
	v_mul_f32_e32 v57, 0xbfb8aa3b, v57
	v_exp_f32_e32 v56, v56
	v_exp_f32_e32 v57, v57
	v_add_f32_e32 v56, 1.0, v56
	v_add_f32_e32 v57, 1.0, v57
	v_rcp_f32_e32 v56, v56
	v_rcp_f32_e32 v57, v57
	s_nop 0
	v_pk_mul_f32 v[56:57], v[58:59], v[56:57]
	s_nop 0
	v_cvt_pk_bf16_f32 v63, v56, v57
	v_lshl_add_u64 v[56:57], s[56:57], 0, v[74:75]
	v_lshl_add_u64 v[56:57], v[56:57], 0, v[66:67]
	global_store_dwordx4 v[56:57], v[60:63], off
	s_nop 1
	s_waitcnt vmcnt(16)
	v_lshlrev_b32_e32 v62, 16, v180
	v_and_b32_e32 v58, 0xffff0000, v180
	v_max_f32_e32 v62, v62, v62
	v_max_f32_e32 v58, v58, v58
	v_med3_f32 v62, v62, s72, v204
	v_med3_f32 v58, v58, s72, v204
	v_mul_f32_e32 v62, 0xbfb8aa3b, v62
	v_mul_f32_e32 v58, 0xbfb8aa3b, v58
	v_exp_f32_e32 v62, v62
	v_exp_f32_e32 v58, v58
	v_add_f32_e32 v62, 1.0, v62
	v_add_f32_e32 v58, 1.0, v58
	v_rcp_f32_e32 v62, v62
	v_rcp_f32_e32 v63, v58
	s_nop 0
	v_pk_mul_f32 v[52:53], v[52:53], v[62:63]
	s_nop 0
	v_cvt_pk_bf16_f32 v52, v52, v53
	v_lshlrev_b32_e32 v53, 16, v181
	v_max_f32_e32 v53, v53, v53
	v_med3_f32 v53, v53, s72, v204
	v_mul_f32_e32 v53, 0xbfb8aa3b, v53
	v_exp_f32_e32 v53, v53
	s_nop 0
	v_add_f32_e32 v53, 1.0, v53
	v_rcp_f32_e32 v58, v53
	v_and_b32_e32 v53, 0xffff0000, v181
	v_max_f32_e32 v53, v53, v53
	v_med3_f32 v53, v53, s72, v204
	v_mul_f32_e32 v53, 0xbfb8aa3b, v53
	v_exp_f32_e32 v53, v53
	s_nop 0
	v_add_f32_e32 v53, 1.0, v53
	v_rcp_f32_e32 v59, v53
	s_nop 0
	v_pk_mul_f32 v[54:55], v[54:55], v[58:59]
	s_nop 0
	v_cvt_pk_bf16_f32 v53, v54, v55
	v_lshlrev_b32_e32 v54, 16, v182
	v_and_b32_e32 v55, 0xffff0000, v182
	v_max_f32_e32 v54, v54, v54
	v_max_f32_e32 v55, v55, v55
	v_med3_f32 v54, v54, s72, v204
	v_med3_f32 v55, v55, s72, v204
	v_mul_f32_e32 v54, 0xbfb8aa3b, v54
	v_mul_f32_e32 v55, 0xbfb8aa3b, v55
	v_exp_f32_e32 v54, v54
	v_exp_f32_e32 v55, v55
	v_add_f32_e32 v54, 1.0, v54
	v_add_f32_e32 v55, 1.0, v55
	v_rcp_f32_e32 v54, v54
	v_rcp_f32_e32 v55, v55
	s_nop 0
	v_pk_mul_f32 v[48:49], v[48:49], v[54:55]
	s_nop 0
	v_cvt_pk_bf16_f32 v54, v48, v49
	v_lshlrev_b32_e32 v48, 16, v183
	v_and_b32_e32 v49, 0xffff0000, v183
	v_max_f32_e32 v48, v48, v48
	v_max_f32_e32 v49, v49, v49
	v_med3_f32 v48, v48, s72, v204
	v_med3_f32 v49, v49, s72, v204
	v_mul_f32_e32 v48, 0xbfb8aa3b, v48
	v_mul_f32_e32 v49, 0xbfb8aa3b, v49
	v_exp_f32_e32 v48, v48
	v_exp_f32_e32 v49, v49
	v_add_f32_e32 v48, 1.0, v48
	v_add_f32_e32 v49, 1.0, v49
	v_rcp_f32_e32 v48, v48
	v_rcp_f32_e32 v49, v49
	s_nop 0
	v_pk_mul_f32 v[48:49], v[50:51], v[48:49]
	s_nop 0
	v_cvt_pk_bf16_f32 v55, v48, v49
	v_add_u32_e32 v48, 0x90, v132
	v_ashrrev_i32_e32 v49, 31, v48
	global_store_dwordx4 v[56:57], v[52:55], off offset:256
	s_nop 1
	v_lshlrev_b64 v[54:55], 11, v[48:49]
	v_lshl_add_u64 v[48:49], s[46:47], 0, v[54:55]
	v_lshl_add_u64 v[48:49], v[48:49], 0, v[66:67]
	s_nop 1
	s_waitcnt vmcnt(14)
	v_lshlrev_b32_e32 v56, 16, v184
	v_and_b32_e32 v50, 0xffff0000, v184
	v_max_f32_e32 v56, v56, v56
	v_max_f32_e32 v50, v50, v50
	v_med3_f32 v56, v56, s72, v204
	v_med3_f32 v50, v50, s72, v204
	v_mul_f32_e32 v56, 0xbfb8aa3b, v56
	v_mul_f32_e32 v50, 0xbfb8aa3b, v50
	v_exp_f32_e32 v56, v56
	v_exp_f32_e32 v50, v50
	v_add_f32_e32 v56, 1.0, v56
	v_add_f32_e32 v50, 1.0, v50
	v_rcp_f32_e32 v56, v56
	v_rcp_f32_e32 v57, v50
	s_nop 0
	v_pk_mul_f32 v[44:45], v[44:45], v[56:57]
	s_nop 0
	v_cvt_pk_bf16_f32 v44, v44, v45
	v_lshlrev_b32_e32 v45, 16, v185
	v_max_f32_e32 v45, v45, v45
	v_med3_f32 v45, v45, s72, v204
	v_mul_f32_e32 v45, 0xbfb8aa3b, v45
	v_exp_f32_e32 v45, v45
	s_nop 0
	v_add_f32_e32 v45, 1.0, v45
	v_rcp_f32_e32 v50, v45
	v_and_b32_e32 v45, 0xffff0000, v185
	v_max_f32_e32 v45, v45, v45
	v_med3_f32 v45, v45, s72, v204
	v_mul_f32_e32 v45, 0xbfb8aa3b, v45
	v_exp_f32_e32 v45, v45
	s_nop 0
	v_add_f32_e32 v45, 1.0, v45
	v_rcp_f32_e32 v51, v45
	s_nop 0
	v_pk_mul_f32 v[46:47], v[46:47], v[50:51]
	s_nop 0
	v_cvt_pk_bf16_f32 v45, v46, v47
	v_lshlrev_b32_e32 v46, 16, v186
	v_and_b32_e32 v47, 0xffff0000, v186
	v_max_f32_e32 v46, v46, v46
	v_max_f32_e32 v47, v47, v47
	v_med3_f32 v46, v46, s72, v204
	v_med3_f32 v47, v47, s72, v204
	v_mul_f32_e32 v46, 0xbfb8aa3b, v46
	v_mul_f32_e32 v47, 0xbfb8aa3b, v47
	v_exp_f32_e32 v46, v46
	v_exp_f32_e32 v47, v47
	v_add_f32_e32 v46, 1.0, v46
	v_add_f32_e32 v47, 1.0, v47
	v_rcp_f32_e32 v46, v46
	v_rcp_f32_e32 v47, v47
	s_nop 0
	v_pk_mul_f32 v[40:41], v[40:41], v[46:47]
	s_nop 0
	v_cvt_pk_bf16_f32 v46, v40, v41
	v_lshlrev_b32_e32 v40, 16, v187
	v_and_b32_e32 v41, 0xffff0000, v187
	v_max_f32_e32 v40, v40, v40
	v_max_f32_e32 v41, v41, v41
	v_med3_f32 v40, v40, s72, v204
	v_med3_f32 v41, v41, s72, v204
	v_mul_f32_e32 v40, 0xbfb8aa3b, v40
	v_mul_f32_e32 v41, 0xbfb8aa3b, v41
	v_exp_f32_e32 v40, v40
	v_exp_f32_e32 v41, v41
	v_add_f32_e32 v40, 1.0, v40
	v_add_f32_e32 v41, 1.0, v41
	v_rcp_f32_e32 v40, v40
	v_rcp_f32_e32 v41, v41
	s_nop 0
	v_pk_mul_f32 v[40:41], v[42:43], v[40:41]
	s_nop 0
	v_cvt_pk_bf16_f32 v47, v40, v41
	v_lshl_add_u64 v[40:41], s[56:57], 0, v[54:55]
	v_lshl_add_u64 v[40:41], v[40:41], 0, v[66:67]
	global_store_dwordx4 v[40:41], v[44:47], off
	s_nop 1
	s_waitcnt vmcnt(16)
	v_lshlrev_b32_e32 v46, 16, v190
	v_and_b32_e32 v42, 0xffff0000, v190
	v_max_f32_e32 v46, v46, v46
	v_max_f32_e32 v42, v42, v42
	v_med3_f32 v46, v46, s72, v204
	v_med3_f32 v42, v42, s72, v204
	v_mul_f32_e32 v46, 0xbfb8aa3b, v46
	v_mul_f32_e32 v42, 0xbfb8aa3b, v42
	v_exp_f32_e32 v46, v46
	v_exp_f32_e32 v42, v42
	v_add_f32_e32 v46, 1.0, v46
	v_add_f32_e32 v42, 1.0, v42
	v_rcp_f32_e32 v46, v46
	v_rcp_f32_e32 v47, v42
	s_nop 0
	v_pk_mul_f32 v[36:37], v[36:37], v[46:47]
	s_nop 0
	v_cvt_pk_bf16_f32 v36, v36, v37
	v_lshlrev_b32_e32 v37, 16, v191
	v_max_f32_e32 v37, v37, v37
	v_med3_f32 v37, v37, s72, v204
	v_mul_f32_e32 v37, 0xbfb8aa3b, v37
	v_exp_f32_e32 v37, v37
	s_nop 0
	v_add_f32_e32 v37, 1.0, v37
	v_rcp_f32_e32 v42, v37
	v_and_b32_e32 v37, 0xffff0000, v191
	v_max_f32_e32 v37, v37, v37
	v_med3_f32 v37, v37, s72, v204
	v_mul_f32_e32 v37, 0xbfb8aa3b, v37
	v_exp_f32_e32 v37, v37
	s_nop 0
	v_add_f32_e32 v37, 1.0, v37
	v_rcp_f32_e32 v43, v37
	s_nop 0
	v_pk_mul_f32 v[38:39], v[38:39], v[42:43]
	s_nop 0
	v_cvt_pk_bf16_f32 v37, v38, v39
	v_lshlrev_b32_e32 v38, 16, v192
	v_and_b32_e32 v39, 0xffff0000, v192
	v_max_f32_e32 v38, v38, v38
	v_max_f32_e32 v39, v39, v39
	v_med3_f32 v38, v38, s72, v204
	v_med3_f32 v39, v39, s72, v204
	v_mul_f32_e32 v38, 0xbfb8aa3b, v38
	v_mul_f32_e32 v39, 0xbfb8aa3b, v39
	v_exp_f32_e32 v38, v38
	v_exp_f32_e32 v39, v39
	v_add_f32_e32 v38, 1.0, v38
	v_add_f32_e32 v39, 1.0, v39
	v_rcp_f32_e32 v38, v38
	v_rcp_f32_e32 v39, v39
	s_nop 0
	v_pk_mul_f32 v[32:33], v[32:33], v[38:39]
	s_nop 0
	v_cvt_pk_bf16_f32 v38, v32, v33
	v_lshlrev_b32_e32 v32, 16, v193
	v_and_b32_e32 v33, 0xffff0000, v193
	v_max_f32_e32 v32, v32, v32
	v_max_f32_e32 v33, v33, v33
	v_med3_f32 v32, v32, s72, v204
	v_med3_f32 v33, v33, s72, v204
	v_mul_f32_e32 v32, 0xbfb8aa3b, v32
	v_mul_f32_e32 v33, 0xbfb8aa3b, v33
	v_exp_f32_e32 v32, v32
	v_exp_f32_e32 v33, v33
	v_add_f32_e32 v32, 1.0, v32
	v_add_f32_e32 v33, 1.0, v33
	v_rcp_f32_e32 v32, v32
	v_rcp_f32_e32 v33, v33
	s_nop 0
	v_pk_mul_f32 v[32:33], v[34:35], v[32:33]
	s_nop 0
	v_cvt_pk_bf16_f32 v39, v32, v33
	v_add_u32_e32 v32, 0xa0, v132
	v_ashrrev_i32_e32 v33, 31, v32
	global_store_dwordx4 v[40:41], v[36:39], off offset:256
	s_nop 1
	v_lshlrev_b64 v[38:39], 11, v[32:33]
	v_lshl_add_u64 v[32:33], s[46:47], 0, v[38:39]
	v_lshl_add_u64 v[32:33], v[32:33], 0, v[66:67]
	s_nop 1
	s_waitcnt vmcnt(14)
	v_lshlrev_b32_e32 v40, 16, v194
	v_and_b32_e32 v34, 0xffff0000, v194
	v_max_f32_e32 v40, v40, v40
	v_max_f32_e32 v34, v34, v34
	v_med3_f32 v40, v40, s72, v204
	v_med3_f32 v34, v34, s72, v204
	v_mul_f32_e32 v40, 0xbfb8aa3b, v40
	v_mul_f32_e32 v34, 0xbfb8aa3b, v34
	v_exp_f32_e32 v40, v40
	v_exp_f32_e32 v34, v34
	v_add_f32_e32 v40, 1.0, v40
	v_add_f32_e32 v34, 1.0, v34
	v_rcp_f32_e32 v40, v40
	v_rcp_f32_e32 v41, v34
	s_nop 0
	v_pk_mul_f32 v[28:29], v[28:29], v[40:41]
	s_nop 0
	v_cvt_pk_bf16_f32 v34, v28, v29
	v_lshlrev_b32_e32 v28, 16, v195
	v_and_b32_e32 v29, 0xffff0000, v195
	v_max_f32_e32 v28, v28, v28
	v_max_f32_e32 v29, v29, v29
	v_med3_f32 v28, v28, s72, v204
	v_med3_f32 v29, v29, s72, v204
	v_mul_f32_e32 v28, 0xbfb8aa3b, v28
	v_mul_f32_e32 v29, 0xbfb8aa3b, v29
	v_exp_f32_e32 v28, v28
	v_exp_f32_e32 v29, v29
	v_add_f32_e32 v28, 1.0, v28
	v_add_f32_e32 v29, 1.0, v29
	v_rcp_f32_e32 v28, v28
	v_rcp_f32_e32 v29, v29
	s_nop 0
	v_pk_mul_f32 v[28:29], v[30:31], v[28:29]
	s_nop 0
	v_cvt_pk_bf16_f32 v35, v28, v29
	v_lshlrev_b32_e32 v28, 16, v196
	v_and_b32_e32 v29, 0xffff0000, v196
	v_max_f32_e32 v28, v28, v28
	v_max_f32_e32 v29, v29, v29
	v_med3_f32 v28, v28, s72, v204
	v_med3_f32 v29, v29, s72, v204
	v_mul_f32_e32 v28, 0xbfb8aa3b, v28
	v_mul_f32_e32 v29, 0xbfb8aa3b, v29
	v_exp_f32_e32 v28, v28
	v_exp_f32_e32 v29, v29
	v_add_f32_e32 v28, 1.0, v28
	v_add_f32_e32 v29, 1.0, v29
	v_rcp_f32_e32 v28, v28
	v_rcp_f32_e32 v29, v29
	s_nop 0
	v_pk_mul_f32 v[24:25], v[24:25], v[28:29]
	s_nop 0
	v_cvt_pk_bf16_f32 v36, v24, v25
	v_lshlrev_b32_e32 v24, 16, v197
	v_and_b32_e32 v25, 0xffff0000, v197
	v_max_f32_e32 v24, v24, v24
	v_max_f32_e32 v25, v25, v25
	v_med3_f32 v24, v24, s72, v204
	v_med3_f32 v25, v25, s72, v204
	v_mul_f32_e32 v24, 0xbfb8aa3b, v24
	v_mul_f32_e32 v25, 0xbfb8aa3b, v25
	v_exp_f32_e32 v24, v24
	v_exp_f32_e32 v25, v25
	v_add_f32_e32 v24, 1.0, v24
	v_add_f32_e32 v25, 1.0, v25
	v_rcp_f32_e32 v24, v24
	v_rcp_f32_e32 v25, v25
	s_nop 0
	v_pk_mul_f32 v[24:25], v[26:27], v[24:25]
	s_nop 0
	v_cvt_pk_bf16_f32 v37, v24, v25
	v_lshl_add_u64 v[24:25], s[56:57], 0, v[38:39]
	v_lshl_add_u64 v[28:29], v[24:25], 0, v[66:67]
	s_nop 1
	s_waitcnt vmcnt(15)
	v_lshlrev_b32_e32 v30, 16, v198
	v_and_b32_e32 v24, 0xffff0000, v198
	v_max_f32_e32 v30, v30, v30
	v_max_f32_e32 v24, v24, v24
	v_med3_f32 v30, v30, s72, v204
	v_med3_f32 v24, v24, s72, v204
	v_mul_f32_e32 v30, 0xbfb8aa3b, v30
	v_mul_f32_e32 v24, 0xbfb8aa3b, v24
	v_exp_f32_e32 v30, v30
	v_exp_f32_e32 v24, v24
	global_store_dwordx4 v[28:29], v[34:37], off
	v_add_f32_e32 v30, 1.0, v30
	v_add_f32_e32 v24, 1.0, v24
	v_rcp_f32_e32 v30, v30
	v_rcp_f32_e32 v31, v24
	s_nop 0
	v_pk_mul_f32 v[20:21], v[20:21], v[30:31]
	s_nop 0
	v_cvt_pk_bf16_f32 v20, v20, v21
	v_lshlrev_b32_e32 v21, 16, v199
	v_max_f32_e32 v21, v21, v21
	v_med3_f32 v21, v21, s72, v204
	v_mul_f32_e32 v21, 0xbfb8aa3b, v21
	v_exp_f32_e32 v21, v21
	s_nop 0
	v_add_f32_e32 v21, 1.0, v21
	v_rcp_f32_e32 v24, v21
	v_and_b32_e32 v21, 0xffff0000, v199
	v_max_f32_e32 v21, v21, v21
	v_med3_f32 v21, v21, s72, v204
	v_mul_f32_e32 v21, 0xbfb8aa3b, v21
	v_exp_f32_e32 v21, v21
	s_nop 0
	v_add_f32_e32 v21, 1.0, v21
	v_rcp_f32_e32 v25, v21
	s_nop 0
	v_pk_mul_f32 v[22:23], v[22:23], v[24:25]
	s_nop 0
	v_cvt_pk_bf16_f32 v21, v22, v23
	v_lshlrev_b32_e32 v22, 16, v200
	v_and_b32_e32 v23, 0xffff0000, v200
	v_max_f32_e32 v22, v22, v22
	v_max_f32_e32 v23, v23, v23
	v_med3_f32 v22, v22, s72, v204
	v_med3_f32 v23, v23, s72, v204
	v_mul_f32_e32 v22, 0xbfb8aa3b, v22
	v_mul_f32_e32 v23, 0xbfb8aa3b, v23
	v_exp_f32_e32 v22, v22
	v_exp_f32_e32 v23, v23
	v_add_f32_e32 v22, 1.0, v22
	v_add_f32_e32 v23, 1.0, v23
	v_rcp_f32_e32 v22, v22
	v_rcp_f32_e32 v23, v23
	s_nop 0
	v_pk_mul_f32 v[16:17], v[16:17], v[22:23]
	s_nop 0
	v_cvt_pk_bf16_f32 v22, v16, v17
	v_lshlrev_b32_e32 v16, 16, v201
	v_and_b32_e32 v17, 0xffff0000, v201
	v_max_f32_e32 v16, v16, v16
	v_max_f32_e32 v17, v17, v17
	v_med3_f32 v16, v16, s72, v204
	v_med3_f32 v17, v17, s72, v204
	v_mul_f32_e32 v16, 0xbfb8aa3b, v16
	v_mul_f32_e32 v17, 0xbfb8aa3b, v17
	v_exp_f32_e32 v16, v16
	v_exp_f32_e32 v17, v17
	v_add_f32_e32 v16, 1.0, v16
	v_add_f32_e32 v17, 1.0, v17
	v_rcp_f32_e32 v16, v16
	v_rcp_f32_e32 v17, v17
	s_nop 0
	v_pk_mul_f32 v[16:17], v[18:19], v[16:17]
	s_nop 0
	v_cvt_pk_bf16_f32 v23, v16, v17
	v_add_u32_e32 v16, 0xb0, v132
	v_ashrrev_i32_e32 v17, 31, v16
	global_store_dwordx4 v[28:29], v[20:23], off offset:256
	s_nop 1
	v_lshlrev_b64 v[22:23], 11, v[16:17]
	v_lshl_add_u64 v[16:17], s[46:47], 0, v[22:23]
	v_lshl_add_u64 v[16:17], v[16:17], 0, v[66:67]
	s_nop 1
	s_waitcnt vmcnt(14)
	v_lshlrev_b32_e32 v24, 16, v214
	v_and_b32_e32 v18, 0xffff0000, v214
	v_max_f32_e32 v24, v24, v24
	v_max_f32_e32 v18, v18, v18
	v_med3_f32 v24, v24, s72, v204
	v_med3_f32 v18, v18, s72, v204
	v_mul_f32_e32 v24, 0xbfb8aa3b, v24
	v_mul_f32_e32 v18, 0xbfb8aa3b, v18
	v_exp_f32_e32 v24, v24
	v_exp_f32_e32 v18, v18
	v_add_f32_e32 v24, 1.0, v24
	v_add_f32_e32 v18, 1.0, v18
	v_rcp_f32_e32 v24, v24
	v_rcp_f32_e32 v25, v18
	s_nop 0
	v_pk_mul_f32 v[12:13], v[12:13], v[24:25]
	s_nop 0
	v_cvt_pk_bf16_f32 v18, v12, v13
	v_lshlrev_b32_e32 v12, 16, v215
	v_and_b32_e32 v13, 0xffff0000, v215
	v_max_f32_e32 v12, v12, v12
	v_max_f32_e32 v13, v13, v13
	v_med3_f32 v12, v12, s72, v204
	v_med3_f32 v13, v13, s72, v204
	v_mul_f32_e32 v12, 0xbfb8aa3b, v12
	v_mul_f32_e32 v13, 0xbfb8aa3b, v13
	v_exp_f32_e32 v12, v12
	v_exp_f32_e32 v13, v13
	v_add_f32_e32 v12, 1.0, v12
	v_add_f32_e32 v13, 1.0, v13
	v_rcp_f32_e32 v12, v12
	v_rcp_f32_e32 v13, v13
	s_nop 0
	v_pk_mul_f32 v[12:13], v[14:15], v[12:13]
	s_nop 0
	v_cvt_pk_bf16_f32 v19, v12, v13
	v_lshlrev_b32_e32 v12, 16, v216
	v_and_b32_e32 v13, 0xffff0000, v216
	v_max_f32_e32 v12, v12, v12
	v_max_f32_e32 v13, v13, v13
	v_med3_f32 v12, v12, s72, v204
	v_med3_f32 v13, v13, s72, v204
	v_mul_f32_e32 v12, 0xbfb8aa3b, v12
	v_mul_f32_e32 v13, 0xbfb8aa3b, v13
	v_exp_f32_e32 v12, v12
	v_exp_f32_e32 v13, v13
	v_add_f32_e32 v12, 1.0, v12
	v_add_f32_e32 v13, 1.0, v13
	v_rcp_f32_e32 v12, v12
	v_rcp_f32_e32 v13, v13
	s_nop 0
	v_pk_mul_f32 v[8:9], v[8:9], v[12:13]
	s_nop 0
	v_cvt_pk_bf16_f32 v20, v8, v9
	v_lshlrev_b32_e32 v8, 16, v217
	v_and_b32_e32 v9, 0xffff0000, v217
	v_max_f32_e32 v8, v8, v8
	v_max_f32_e32 v9, v9, v9
	v_med3_f32 v8, v8, s72, v204
	v_med3_f32 v9, v9, s72, v204
	v_mul_f32_e32 v8, 0xbfb8aa3b, v8
	v_mul_f32_e32 v9, 0xbfb8aa3b, v9
	v_exp_f32_e32 v8, v8
	v_exp_f32_e32 v9, v9
	v_add_f32_e32 v8, 1.0, v8
	v_add_f32_e32 v9, 1.0, v9
	v_rcp_f32_e32 v8, v8
	v_rcp_f32_e32 v9, v9
	s_nop 0
	v_pk_mul_f32 v[8:9], v[10:11], v[8:9]
	s_nop 0
	v_cvt_pk_bf16_f32 v21, v8, v9
	v_lshl_add_u64 v[8:9], s[56:57], 0, v[22:23]
	v_lshl_add_u64 v[12:13], v[8:9], 0, v[66:67]
	s_nop 1
	s_waitcnt vmcnt(15)
	v_lshlrev_b32_e32 v14, 16, v218
	v_and_b32_e32 v8, 0xffff0000, v218
	v_max_f32_e32 v14, v14, v14
	v_max_f32_e32 v8, v8, v8
	v_med3_f32 v14, v14, s72, v204
	v_med3_f32 v8, v8, s72, v204
	v_mul_f32_e32 v14, 0xbfb8aa3b, v14
	v_mul_f32_e32 v8, 0xbfb8aa3b, v8
	v_exp_f32_e32 v14, v14
	v_exp_f32_e32 v8, v8
	global_store_dwordx4 v[12:13], v[18:21], off
	v_add_f32_e32 v14, 1.0, v14
	v_add_f32_e32 v8, 1.0, v8
	v_rcp_f32_e32 v14, v14
	v_rcp_f32_e32 v15, v8
	s_nop 0
	v_pk_mul_f32 v[4:5], v[4:5], v[14:15]
	s_nop 0
	v_cvt_pk_bf16_f32 v4, v4, v5
	v_lshlrev_b32_e32 v5, 16, v219
	v_max_f32_e32 v5, v5, v5
	v_med3_f32 v5, v5, s72, v204
	v_mul_f32_e32 v5, 0xbfb8aa3b, v5
	v_exp_f32_e32 v5, v5
	s_nop 0
	v_add_f32_e32 v5, 1.0, v5
	v_rcp_f32_e32 v8, v5
	v_and_b32_e32 v5, 0xffff0000, v219
	v_max_f32_e32 v5, v5, v5
	v_med3_f32 v5, v5, s72, v204
	v_mul_f32_e32 v5, 0xbfb8aa3b, v5
	v_exp_f32_e32 v5, v5
	s_nop 0
	v_add_f32_e32 v5, 1.0, v5
	v_rcp_f32_e32 v9, v5
	s_nop 0
	v_pk_mul_f32 v[6:7], v[6:7], v[8:9]
	s_nop 0
	v_cvt_pk_bf16_f32 v5, v6, v7
	v_lshlrev_b32_e32 v6, 16, v220
	v_and_b32_e32 v7, 0xffff0000, v220
	v_max_f32_e32 v6, v6, v6
	v_max_f32_e32 v7, v7, v7
	v_med3_f32 v6, v6, s72, v204
	v_med3_f32 v7, v7, s72, v204
	v_mul_f32_e32 v6, 0xbfb8aa3b, v6
	v_mul_f32_e32 v7, 0xbfb8aa3b, v7
	v_exp_f32_e32 v6, v6
	v_exp_f32_e32 v7, v7
	v_add_f32_e32 v6, 1.0, v6
	v_add_f32_e32 v7, 1.0, v7
	v_rcp_f32_e32 v6, v6
	v_rcp_f32_e32 v7, v7
	s_nop 0
	v_pk_mul_f32 v[0:1], v[0:1], v[6:7]
	s_nop 0
	v_cvt_pk_bf16_f32 v6, v0, v1
	v_lshlrev_b32_e32 v0, 16, v221
	v_and_b32_e32 v1, 0xffff0000, v221
	v_max_f32_e32 v0, v0, v0
	v_max_f32_e32 v1, v1, v1
	v_med3_f32 v0, v0, s72, v204
	v_med3_f32 v1, v1, s72, v204
	v_mul_f32_e32 v0, 0xbfb8aa3b, v0
	v_mul_f32_e32 v1, 0xbfb8aa3b, v1
	v_exp_f32_e32 v0, v0
	v_exp_f32_e32 v1, v1
	v_add_f32_e32 v0, 1.0, v0
	v_add_f32_e32 v1, 1.0, v1
	v_rcp_f32_e32 v0, v0
	v_rcp_f32_e32 v1, v1
	s_nop 0
	v_pk_mul_f32 v[0:1], v[2:3], v[0:1]
	s_nop 0
	v_cvt_pk_bf16_f32 v7, v0, v1
	global_store_dwordx4 v[12:13], v[4:7], off offset:256
	s_cbranch_vccnz .LBB0_141
	s_andn2_b64 vcc, exec, s[0:1]
	s_cbranch_vccnz .LBB0_140
	s_barrier
	s_branch .LBB0_140

.LBB0_253:
	v_mov_b32_e32 v64, v203
	s_add_i32 s22, s22, s59
	s_mov_b32 s17, s51
	v_and_or_b32 v130, v64, 15, s22
	s_or_b32 s2, s7, s51
	v_readlane_b32 s50, v254, 54
	v_ashrrev_i32_e32 v131, 31, v130
	v_readlane_b32 s51, v254, 55
	v_lshrrev_b32_e32 v64, 2, v64
	v_and_b32_e32 v150, 12, v64
	v_lshl_add_u64 v[132:133], v[130:131], 2, s[50:51]
	v_mov_b32_e32 v152, v132
	v_mov_b32_e32 v153, v133
	global_load_dword v64, v[132:133], off
	global_load_dword v154, v[152:153], off offset:64
	global_load_dword v156, v[152:153], off offset:128
	global_load_dword v158, v[152:153], off offset:192
	global_load_dword v160, v[152:153], off offset:512
	global_load_dword v162, v[152:153], off offset:576
	global_load_dword v164, v[152:153], off offset:640
	global_load_dword v166, v[152:153], off offset:704
	v_readlane_b32 s52, v254, 56
	v_lshlrev_b64 v[138:139], 6, v[130:131]
	v_readlane_b32 s53, v254, 57
	s_ashr_i32 s3, s2, 5
	s_mul_hi_i32 s7, s3, 0x55555556
	v_lshl_add_u64 v[134:135], s[52:53], 0, v[138:139]
	v_lshl_add_u64 v[138:139], s[82:83], 0, v[138:139]
	s_lshr_b32 s10, s7, 31
	s_add_i32 s7, s7, s10
	s_mul_i32 s7, s7, 3
	s_sub_i32 s3, s3, s7
	s_cmp_eq_u32 s3, 2
	s_cselect_b64 s[40:41], -1, 0
	s_ashr_i32 s3, s2, 31
	v_readlane_b32 s10, v254, 52
	s_lshl_b64 s[56:57], s[2:3], 1
	s_bitset1_b32 s2, 7
	v_readlane_b32 s11, v254, 53
	s_ashr_i32 s2, s2, 5
	s_mul_hi_i32 s3, s2, 0x55555556
	s_lshr_b32 s7, s3, 31
	s_add_i32 s3, s3, s7
	s_mul_i32 s3, s3, 3
	s_sub_i32 s2, s2, s3
	s_cmp_eq_u32 s2, 2
	s_cselect_b64 vcc, -1, 0
	s_mov_b32 s27, 0x42b17218
	v_readlane_b32 s71, v254, 49
	v_readlane_b32 s48, v255, 50
	s_waitcnt vmcnt(7)
	v_mul_f32_e32 v132, 0x3e16c740, v64
	v_lshlrev_b32_e32 v64, 2, v150
	v_lshl_add_u64 v[134:135], v[134:135], 0, v[64:65]
	v_lshl_add_u64 v[138:139], v[138:139], 0, v[64:65]
	v_mov_b32_e32 v168, v134
	v_mov_b32_e32 v169, v135
	global_load_dwordx4 v[134:137], v[134:135], off
	global_load_dwordx4 v[170:173], v[168:169], off offset:1024
	global_load_dwordx4 v[174:177], v[168:169], off offset:2048
	global_load_dwordx4 v[178:181], v[168:169], off offset:3072
	s_mov_b64 s[98:99], 0x2000
	v_lshl_add_u64 v[182:183], v[168:169], 0, s[98:99]
	global_load_dwordx4 v[182:185], v[182:183], off
	s_mov_b64 s[98:99], 0x2400
	v_lshl_add_u64 v[190:191], v[168:169], 0, s[98:99]
	global_load_dwordx4 v[190:193], v[190:191], off
	s_mov_b64 s[98:99], 0x2800
	v_lshl_add_u64 v[194:195], v[168:169], 0, s[98:99]
	global_load_dwordx4 v[194:197], v[194:195], off
	s_mov_b64 s[98:99], 0x2c00
	v_lshl_add_u64 v[198:199], v[168:169], 0, s[98:99]
	global_load_dwordx4 v[198:201], v[198:199], off
	v_pk_mul_f32 v[126:127], v[126:127], v[132:133] op_sel_hi:[1,0]
	v_mov_b32_e32 v186, v138
	v_mov_b32_e32 v187, v139
	global_load_dwordx4 v[138:141], v[138:139], off
	global_load_dwordx4 v[214:217], v[186:187], off offset:1024
	global_load_dwordx4 v[218:221], v[186:187], off offset:2048
	global_load_dwordx4 v[222:225], v[186:187], off offset:3072
	s_mov_b64 s[98:99], 0x2000
	v_lshl_add_u64 v[226:227], v[186:187], 0, s[98:99]
	global_load_dwordx4 v[226:229], v[226:227], off
	s_mov_b64 s[98:99], 0x2400
	v_lshl_add_u64 v[230:231], v[186:187], 0, s[98:99]
	global_load_dwordx4 v[230:233], v[230:231], off
	s_mov_b64 s[98:99], 0x2800
	v_lshl_add_u64 v[234:235], v[186:187], 0, s[98:99]
	global_load_dwordx4 v[234:237], v[234:235], off
	s_mov_b64 s[98:99], 0x2c00
	v_lshl_add_u64 v[238:239], v[186:187], 0, s[98:99]
	global_load_dwordx4 v[238:241], v[238:239], off
	v_pk_mul_f32 v[122:123], v[122:123], v[132:133] op_sel_hi:[1,0]
	v_pk_mul_f32 v[128:129], v[128:129], v[132:133] op_sel_hi:[1,0]
	v_pk_mul_f32 v[124:125], v[124:125], v[132:133] op_sel_hi:[1,0]
	s_waitcnt vmcnt(15)
	v_pk_mul_f32 v[146:147], v[134:135], v[126:127]
	v_pk_mul_f32 v[148:149], v[136:137], v[128:129]
	s_waitcnt vmcnt(7)
	v_pk_mul_f32 v[142:143], v[138:139], v[126:127]
	v_pk_mul_f32 v[144:145], v[140:141], v[128:129]
	v_pk_fma_f32 v[142:143], v[134:135], v[122:123], v[142:143] neg_lo:[0,0,1] neg_hi:[0,0,1]
	v_pk_fma_f32 v[144:145], v[136:137], v[124:125], v[144:145] neg_lo:[0,0,1] neg_hi:[0,0,1]
	v_pk_fma_f32 v[146:147], v[138:139], v[122:123], v[146:147]
	v_cndmask_b32_e64 v123, v123, v143, s[40:41]
	v_cndmask_b32_e64 v122, v122, v142, s[40:41]
	v_pk_fma_f32 v[148:149], v[140:141], v[124:125], v[148:149]
	v_cndmask_b32_e64 v125, v125, v145, s[40:41]
	v_cndmask_b32_e64 v124, v124, v144, s[40:41]
	v_cndmask_b32_e64 v143, v126, v146, s[40:41]
	v_cvt_pk_bf16_f32 v126, v122, v123
	v_mov_b64_e32 v[122:123], s[10:11]
	v_cndmask_b32_e64 v142, v127, v147, s[40:41]
	v_cvt_pk_bf16_f32 v127, v124, v125
	v_mad_i64_i32 v[124:125], s[10:11], v130, s33, v[122:123]
	v_cndmask_b32_e64 v131, v129, v149, s[40:41]
	v_cndmask_b32_e64 v133, v128, v148, s[40:41]
	v_lshl_add_u64 v[128:129], v[124:125], 0, s[56:57]
	v_lshlrev_b32_e32 v124, 1, v150
	v_mov_b32_e32 v125, v65
	v_lshl_add_u64 v[128:129], v[128:129], 0, v[124:125]
	global_store_dwordx2 v[128:129], v[126:127], off
	v_cvt_pk_bf16_f32 v126, v143, v142
	v_cvt_pk_bf16_f32 v127, v133, v131
	v_pk_mul_f32 v[118:119], v[118:119], v[132:133] op_sel_hi:[1,0]
	v_pk_mul_f32 v[120:121], v[120:121], v[132:133] op_sel_hi:[1,0]
	global_store_dwordx2 v[128:129], v[126:127], off offset:32
	v_pk_mul_f32 v[114:115], v[114:115], v[132:133] op_sel_hi:[1,0]
	v_pk_mul_f32 v[116:117], v[116:117], v[132:133] op_sel_hi:[1,0]
	v_pk_mul_f32 v[126:127], v[138:139], v[118:119]
	v_pk_mul_f32 v[132:133], v[140:141], v[120:121]
	v_pk_fma_f32 v[126:127], v[134:135], v[114:115], v[126:127] neg_lo:[0,0,1] neg_hi:[0,0,1]
	v_pk_fma_f32 v[132:133], v[136:137], v[116:117], v[132:133] neg_lo:[0,0,1] neg_hi:[0,0,1]
	v_pk_mul_f32 v[134:135], v[134:135], v[118:119]
	v_pk_mul_f32 v[136:137], v[136:137], v[120:121]
	v_pk_fma_f32 v[134:135], v[138:139], v[114:115], v[134:135]
	v_pk_fma_f32 v[136:137], v[140:141], v[116:117], v[136:137]
	v_cndmask_b32_e32 v117, v117, v133, vcc
	v_cndmask_b32_e32 v116, v116, v132, vcc
	v_cndmask_b32_e32 v115, v115, v127, vcc
	v_cndmask_b32_e32 v114, v114, v126, vcc
	v_cndmask_b32_e32 v121, v121, v137, vcc
	v_cndmask_b32_e32 v120, v120, v136, vcc
	v_cndmask_b32_e32 v119, v119, v135, vcc
	v_cndmask_b32_e32 v118, v118, v134, vcc
	v_cvt_pk_bf16_f32 v114, v114, v115
	v_cvt_pk_bf16_f32 v115, v116, v117
	global_store_dwordx2 v[128:129], v[114:115], off offset:256
	v_cvt_pk_bf16_f32 v114, v118, v119
	v_cvt_pk_bf16_f32 v115, v120, v121
	global_store_dwordx2 v[128:129], v[114:115], off offset:288
	v_or_b32_e32 v114, 16, v130
	v_ashrrev_i32_e32 v115, 31, v114
	v_lshl_add_u64 v[116:117], v[114:115], 2, s[50:51]
	s_nop 1
	v_lshlrev_b64 v[126:127], 6, v[114:115]
	s_waitcnt vmcnt(26)
	v_mul_f32_e32 v120, 0x3e16c740, v154
	v_lshl_add_u64 v[116:117], s[52:53], 0, v[126:127]
	v_lshl_add_u64 v[126:127], s[82:83], 0, v[126:127]
	v_lshl_add_u64 v[116:117], v[116:117], 0, v[64:65]
	v_lshl_add_u64 v[126:127], v[126:127], 0, v[64:65]
	s_nop 1
	v_pk_mul_f32 v[110:111], v[110:111], v[120:121] op_sel_hi:[1,0]
	s_nop 1
	v_pk_mul_f32 v[112:113], v[112:113], v[120:121] op_sel_hi:[1,0]
	v_pk_mul_f32 v[106:107], v[106:107], v[120:121] op_sel_hi:[1,0]
	v_pk_mul_f32 v[108:109], v[108:109], v[120:121] op_sel_hi:[1,0]
	v_pk_mul_f32 v[102:103], v[102:103], v[120:121] op_sel_hi:[1,0]
	v_pk_mul_f32 v[104:105], v[104:105], v[120:121] op_sel_hi:[1,0]
	v_pk_mul_f32 v[98:99], v[98:99], v[120:121] op_sel_hi:[1,0]
	v_pk_mul_f32 v[100:101], v[100:101], v[120:121] op_sel_hi:[1,0]
	s_waitcnt vmcnt(18)
	v_pk_mul_f32 v[136:137], v[170:171], v[110:111]
	v_pk_mul_f32 v[138:139], v[172:173], v[112:113]
	s_waitcnt vmcnt(10)
	v_pk_mul_f32 v[132:133], v[214:215], v[110:111]
	v_pk_mul_f32 v[134:135], v[216:217], v[112:113]
	v_pk_fma_f32 v[132:133], v[170:171], v[106:107], v[132:133] neg_lo:[0,0,1] neg_hi:[0,0,1]
	v_pk_fma_f32 v[134:135], v[172:173], v[108:109], v[134:135] neg_lo:[0,0,1] neg_hi:[0,0,1]
	v_pk_fma_f32 v[138:139], v[216:217], v[108:109], v[138:139]
	v_pk_fma_f32 v[136:137], v[214:215], v[106:107], v[136:137]
	v_cndmask_b32_e64 v109, v109, v135, s[40:41]
	v_cndmask_b32_e64 v108, v108, v134, s[40:41]
	v_cndmask_b32_e64 v107, v107, v133, s[40:41]
	v_cndmask_b32_e64 v106, v106, v132, s[40:41]
	v_cvt_pk_bf16_f32 v106, v106, v107
	v_cvt_pk_bf16_f32 v107, v108, v109
	v_mad_i64_i32 v[108:109], s[2:3], v114, s33, v[122:123]
	v_lshl_add_u64 v[108:109], v[108:109], 0, s[56:57]
	v_cndmask_b32_e64 v113, v113, v139, s[40:41]
	v_cndmask_b32_e64 v112, v112, v138, s[40:41]
	v_cndmask_b32_e64 v111, v111, v137, s[40:41]
	v_cndmask_b32_e64 v110, v110, v136, s[40:41]
	v_lshl_add_u64 v[108:109], v[108:109], 0, v[124:125]
	global_store_dwordx2 v[108:109], v[106:107], off
	v_cvt_pk_bf16_f32 v106, v110, v111
	v_cvt_pk_bf16_f32 v107, v112, v113
	global_store_dwordx2 v[108:109], v[106:107], off offset:32
	v_pk_mul_f32 v[106:107], v[214:215], v[102:103]
	v_pk_mul_f32 v[110:111], v[216:217], v[104:105]
	v_pk_fma_f32 v[106:107], v[170:171], v[98:99], v[106:107] neg_lo:[0,0,1] neg_hi:[0,0,1]
	v_pk_fma_f32 v[110:111], v[172:173], v[100:101], v[110:111] neg_lo:[0,0,1] neg_hi:[0,0,1]
	v_pk_mul_f32 v[112:113], v[170:171], v[102:103]
	v_pk_mul_f32 v[114:115], v[172:173], v[104:105]
	v_pk_fma_f32 v[112:113], v[214:215], v[98:99], v[112:113]
	v_pk_fma_f32 v[114:115], v[216:217], v[100:101], v[114:115]
	v_cndmask_b32_e32 v101, v101, v111, vcc
	v_cndmask_b32_e32 v100, v100, v110, vcc
	v_cndmask_b32_e32 v99, v99, v107, vcc
	v_cndmask_b32_e32 v98, v98, v106, vcc
	v_cndmask_b32_e32 v105, v105, v115, vcc
	v_cndmask_b32_e32 v104, v104, v114, vcc
	v_cndmask_b32_e32 v103, v103, v113, vcc
	v_cndmask_b32_e32 v102, v102, v112, vcc
	v_cvt_pk_bf16_f32 v98, v98, v99
	v_cvt_pk_bf16_f32 v99, v100, v101
	global_store_dwordx2 v[108:109], v[98:99], off offset:256
	v_cvt_pk_bf16_f32 v98, v102, v103
	v_cvt_pk_bf16_f32 v99, v104, v105
	global_store_dwordx2 v[108:109], v[98:99], off offset:288
	v_or_b32_e32 v98, 32, v130
	v_ashrrev_i32_e32 v99, 31, v98
	v_lshl_add_u64 v[100:101], v[98:99], 2, s[50:51]
	s_nop 1
	v_lshlrev_b64 v[104:105], 6, v[98:99]
	s_waitcnt vmcnt(29)
	v_mul_f32_e32 v108, 0x3e16c740, v156
	v_lshl_add_u64 v[100:101], s[52:53], 0, v[104:105]
	v_lshl_add_u64 v[104:105], s[82:83], 0, v[104:105]
	v_lshl_add_u64 v[100:101], v[100:101], 0, v[64:65]
	v_lshl_add_u64 v[104:105], v[104:105], 0, v[64:65]
	s_nop 1
	v_pk_mul_f32 v[94:95], v[94:95], v[108:109] op_sel_hi:[1,0]
	s_nop 1
	v_pk_mul_f32 v[96:97], v[96:97], v[108:109] op_sel_hi:[1,0]
	v_pk_mul_f32 v[90:91], v[90:91], v[108:109] op_sel_hi:[1,0]
	v_pk_mul_f32 v[92:93], v[92:93], v[108:109] op_sel_hi:[1,0]
	v_pk_mul_f32 v[86:87], v[86:87], v[108:109] op_sel_hi:[1,0]
	v_pk_mul_f32 v[88:89], v[88:89], v[108:109] op_sel_hi:[1,0]
	v_pk_mul_f32 v[82:83], v[82:83], v[108:109] op_sel_hi:[1,0]
	v_pk_mul_f32 v[84:85], v[84:85], v[108:109] op_sel_hi:[1,0]
	s_waitcnt vmcnt(21)
	v_pk_mul_f32 v[114:115], v[174:175], v[94:95]
	v_pk_mul_f32 v[116:117], v[176:177], v[96:97]
	s_waitcnt vmcnt(13)
	v_pk_mul_f32 v[110:111], v[218:219], v[94:95]
	v_pk_mul_f32 v[112:113], v[220:221], v[96:97]
	v_pk_fma_f32 v[110:111], v[174:175], v[90:91], v[110:111] neg_lo:[0,0,1] neg_hi:[0,0,1]
	v_pk_fma_f32 v[112:113], v[176:177], v[92:93], v[112:113] neg_lo:[0,0,1] neg_hi:[0,0,1]
	v_pk_fma_f32 v[116:117], v[220:221], v[92:93], v[116:117]
	v_pk_fma_f32 v[114:115], v[218:219], v[90:91], v[114:115]
	v_cndmask_b32_e64 v93, v93, v113, s[40:41]
	v_cndmask_b32_e64 v92, v92, v112, s[40:41]
	v_cndmask_b32_e64 v91, v91, v111, s[40:41]
	v_cndmask_b32_e64 v90, v90, v110, s[40:41]
	v_cvt_pk_bf16_f32 v90, v90, v91
	v_cvt_pk_bf16_f32 v91, v92, v93
	v_mad_i64_i32 v[92:93], s[2:3], v98, s33, v[122:123]
	v_lshl_add_u64 v[92:93], v[92:93], 0, s[56:57]
	v_cndmask_b32_e64 v97, v97, v117, s[40:41]
	v_cndmask_b32_e64 v96, v96, v116, s[40:41]
	v_cndmask_b32_e64 v95, v95, v115, s[40:41]
	v_cndmask_b32_e64 v94, v94, v114, s[40:41]
	v_lshl_add_u64 v[92:93], v[92:93], 0, v[124:125]
	global_store_dwordx2 v[92:93], v[90:91], off
	v_cvt_pk_bf16_f32 v90, v94, v95
	v_cvt_pk_bf16_f32 v91, v96, v97
	global_store_dwordx2 v[92:93], v[90:91], off offset:32
	v_pk_mul_f32 v[90:91], v[218:219], v[86:87]
	v_pk_mul_f32 v[94:95], v[220:221], v[88:89]
	v_pk_fma_f32 v[90:91], v[174:175], v[82:83], v[90:91] neg_lo:[0,0,1] neg_hi:[0,0,1]
	v_pk_fma_f32 v[94:95], v[176:177], v[84:85], v[94:95] neg_lo:[0,0,1] neg_hi:[0,0,1]
	v_pk_mul_f32 v[96:97], v[174:175], v[86:87]
	v_pk_mul_f32 v[98:99], v[176:177], v[88:89]
	v_pk_fma_f32 v[96:97], v[218:219], v[82:83], v[96:97]
	v_pk_fma_f32 v[98:99], v[220:221], v[84:85], v[98:99]
	v_cndmask_b32_e32 v85, v85, v95, vcc
	v_cndmask_b32_e32 v84, v84, v94, vcc
	v_cndmask_b32_e32 v83, v83, v91, vcc
	v_cndmask_b32_e32 v82, v82, v90, vcc
	v_cndmask_b32_e32 v89, v89, v99, vcc
	v_cndmask_b32_e32 v88, v88, v98, vcc
	v_cndmask_b32_e32 v87, v87, v97, vcc
	v_cndmask_b32_e32 v86, v86, v96, vcc
	v_cvt_pk_bf16_f32 v82, v82, v83
	v_cvt_pk_bf16_f32 v83, v84, v85
	global_store_dwordx2 v[92:93], v[82:83], off offset:256
	v_cvt_pk_bf16_f32 v82, v86, v87
	v_cvt_pk_bf16_f32 v83, v88, v89
	global_store_dwordx2 v[92:93], v[82:83], off offset:288
	v_or_b32_e32 v82, 48, v130
	v_ashrrev_i32_e32 v83, 31, v82
	v_lshl_add_u64 v[84:85], v[82:83], 2, s[50:51]
	s_nop 1
	v_lshlrev_b64 v[88:89], 6, v[82:83]
	s_waitcnt vmcnt(32)
	v_mul_f32_e32 v92, 0x3e16c740, v158
	v_lshl_add_u64 v[84:85], s[52:53], 0, v[88:89]
	v_lshl_add_u64 v[88:89], s[82:83], 0, v[88:89]
	v_lshl_add_u64 v[84:85], v[84:85], 0, v[64:65]
	v_lshl_add_u64 v[88:89], v[88:89], 0, v[64:65]
	s_nop 1
	v_pk_mul_f32 v[78:79], v[78:79], v[92:93] op_sel_hi:[1,0]
	s_nop 1
	v_pk_mul_f32 v[80:81], v[80:81], v[92:93] op_sel_hi:[1,0]
	v_pk_mul_f32 v[74:75], v[74:75], v[92:93] op_sel_hi:[1,0]
	v_pk_mul_f32 v[76:77], v[76:77], v[92:93] op_sel_hi:[1,0]
	v_pk_mul_f32 v[70:71], v[70:71], v[92:93] op_sel_hi:[1,0]
	v_pk_mul_f32 v[72:73], v[72:73], v[92:93] op_sel_hi:[1,0]
	v_pk_mul_f32 v[66:67], v[66:67], v[92:93] op_sel_hi:[1,0]
	v_pk_mul_f32 v[68:69], v[68:69], v[92:93] op_sel_hi:[1,0]
	s_waitcnt vmcnt(24)
	v_pk_mul_f32 v[98:99], v[178:179], v[78:79]
	v_pk_mul_f32 v[100:101], v[180:181], v[80:81]
	s_waitcnt vmcnt(16)
	v_pk_mul_f32 v[94:95], v[222:223], v[78:79]
	v_pk_mul_f32 v[96:97], v[224:225], v[80:81]
	v_pk_fma_f32 v[94:95], v[178:179], v[74:75], v[94:95] neg_lo:[0,0,1] neg_hi:[0,0,1]
	v_pk_fma_f32 v[96:97], v[180:181], v[76:77], v[96:97] neg_lo:[0,0,1] neg_hi:[0,0,1]
	v_pk_fma_f32 v[100:101], v[224:225], v[76:77], v[100:101]
	v_pk_fma_f32 v[98:99], v[222:223], v[74:75], v[98:99]
	v_cndmask_b32_e64 v77, v77, v97, s[40:41]
	v_cndmask_b32_e64 v76, v76, v96, s[40:41]
	v_cndmask_b32_e64 v75, v75, v95, s[40:41]
	v_cndmask_b32_e64 v74, v74, v94, s[40:41]
	v_cvt_pk_bf16_f32 v74, v74, v75
	v_cvt_pk_bf16_f32 v75, v76, v77
	v_mad_i64_i32 v[76:77], s[2:3], v82, s33, v[122:123]
	v_lshl_add_u64 v[76:77], v[76:77], 0, s[56:57]
	v_cndmask_b32_e64 v81, v81, v101, s[40:41]
	v_cndmask_b32_e64 v80, v80, v100, s[40:41]
	v_cndmask_b32_e64 v79, v79, v99, s[40:41]
	v_cndmask_b32_e64 v78, v78, v98, s[40:41]
	v_lshl_add_u64 v[76:77], v[76:77], 0, v[124:125]
	global_store_dwordx2 v[76:77], v[74:75], off
	v_cvt_pk_bf16_f32 v74, v78, v79
	v_cvt_pk_bf16_f32 v75, v80, v81
	global_store_dwordx2 v[76:77], v[74:75], off offset:32
	v_pk_mul_f32 v[74:75], v[222:223], v[70:71]
	v_pk_mul_f32 v[78:79], v[224:225], v[72:73]
	v_pk_fma_f32 v[74:75], v[178:179], v[66:67], v[74:75] neg_lo:[0,0,1] neg_hi:[0,0,1]
	v_pk_fma_f32 v[78:79], v[180:181], v[68:69], v[78:79] neg_lo:[0,0,1] neg_hi:[0,0,1]
	v_pk_mul_f32 v[80:81], v[178:179], v[70:71]
	v_pk_mul_f32 v[82:83], v[180:181], v[72:73]
	v_pk_fma_f32 v[80:81], v[222:223], v[66:67], v[80:81]
	v_pk_fma_f32 v[82:83], v[224:225], v[68:69], v[82:83]
	v_cndmask_b32_e32 v69, v69, v79, vcc
	v_cndmask_b32_e32 v68, v68, v78, vcc
	v_cndmask_b32_e32 v67, v67, v75, vcc
	v_cndmask_b32_e32 v66, v66, v74, vcc
	v_cndmask_b32_e32 v73, v73, v83, vcc
	v_cndmask_b32_e32 v72, v72, v82, vcc
	v_cndmask_b32_e32 v71, v71, v81, vcc
	v_cndmask_b32_e32 v70, v70, v80, vcc
	v_cvt_pk_bf16_f32 v66, v66, v67
	v_cvt_pk_bf16_f32 v67, v68, v69
	global_store_dwordx2 v[76:77], v[66:67], off offset:256
	v_cvt_pk_bf16_f32 v66, v70, v71
	v_cvt_pk_bf16_f32 v67, v72, v73
	global_store_dwordx2 v[76:77], v[66:67], off offset:288
	v_add_u32_e32 v66, 0x80, v130
	v_ashrrev_i32_e32 v67, 31, v66
	v_lshl_add_u64 v[68:69], v[66:67], 2, s[50:51]
	s_nop 1
	v_lshlrev_b64 v[72:73], 6, v[66:67]
	s_waitcnt vmcnt(35)
	v_mul_f32_e32 v76, 0x3e16c740, v160
	v_lshl_add_u64 v[68:69], s[52:53], 0, v[72:73]
	v_lshl_add_u64 v[72:73], s[82:83], 0, v[72:73]
	v_lshl_add_u64 v[68:69], v[68:69], 0, v[64:65]
	v_lshl_add_u64 v[72:73], v[72:73], 0, v[64:65]
	s_nop 1
	v_pk_mul_f32 v[60:61], v[60:61], v[76:77] op_sel_hi:[1,0]
	s_nop 1
	v_pk_mul_f32 v[62:63], v[62:63], v[76:77] op_sel_hi:[1,0]
	v_pk_mul_f32 v[56:57], v[56:57], v[76:77] op_sel_hi:[1,0]
	v_pk_mul_f32 v[58:59], v[58:59], v[76:77] op_sel_hi:[1,0]
	v_pk_mul_f32 v[52:53], v[52:53], v[76:77] op_sel_hi:[1,0]
	v_pk_mul_f32 v[54:55], v[54:55], v[76:77] op_sel_hi:[1,0]
	v_pk_mul_f32 v[48:49], v[48:49], v[76:77] op_sel_hi:[1,0]
	v_pk_mul_f32 v[50:51], v[50:51], v[76:77] op_sel_hi:[1,0]
	s_waitcnt vmcnt(27)
	v_pk_mul_f32 v[82:83], v[182:183], v[60:61]
	v_pk_mul_f32 v[84:85], v[184:185], v[62:63]
	s_waitcnt vmcnt(19)
	v_pk_mul_f32 v[78:79], v[226:227], v[60:61]
	v_pk_mul_f32 v[80:81], v[228:229], v[62:63]
	v_pk_fma_f32 v[78:79], v[182:183], v[56:57], v[78:79] neg_lo:[0,0,1] neg_hi:[0,0,1]
	v_pk_fma_f32 v[80:81], v[184:185], v[58:59], v[80:81] neg_lo:[0,0,1] neg_hi:[0,0,1]
	v_pk_fma_f32 v[84:85], v[228:229], v[58:59], v[84:85]
	v_pk_fma_f32 v[82:83], v[226:227], v[56:57], v[82:83]
	v_cndmask_b32_e64 v59, v59, v81, s[40:41]
	v_cndmask_b32_e64 v58, v58, v80, s[40:41]
	v_cndmask_b32_e64 v57, v57, v79, s[40:41]
	v_cndmask_b32_e64 v56, v56, v78, s[40:41]
	v_cvt_pk_bf16_f32 v56, v56, v57
	v_cvt_pk_bf16_f32 v57, v58, v59
	v_mad_i64_i32 v[58:59], s[2:3], v66, s33, v[122:123]
	v_lshl_add_u64 v[58:59], v[58:59], 0, s[56:57]
	v_cndmask_b32_e64 v63, v63, v85, s[40:41]
	v_cndmask_b32_e64 v62, v62, v84, s[40:41]
	v_cndmask_b32_e64 v61, v61, v83, s[40:41]
	v_cndmask_b32_e64 v60, v60, v82, s[40:41]
	v_lshl_add_u64 v[58:59], v[58:59], 0, v[124:125]
	global_store_dwordx2 v[58:59], v[56:57], off
	v_cvt_pk_bf16_f32 v56, v60, v61
	v_cvt_pk_bf16_f32 v57, v62, v63
	global_store_dwordx2 v[58:59], v[56:57], off offset:32
	v_pk_mul_f32 v[56:57], v[226:227], v[52:53]
	v_pk_mul_f32 v[60:61], v[228:229], v[54:55]
	v_pk_fma_f32 v[56:57], v[182:183], v[48:49], v[56:57] neg_lo:[0,0,1] neg_hi:[0,0,1]
	v_pk_fma_f32 v[60:61], v[184:185], v[50:51], v[60:61] neg_lo:[0,0,1] neg_hi:[0,0,1]
	v_pk_mul_f32 v[62:63], v[182:183], v[52:53]
	v_pk_mul_f32 v[66:67], v[184:185], v[54:55]
	v_pk_fma_f32 v[62:63], v[226:227], v[48:49], v[62:63]
	v_pk_fma_f32 v[66:67], v[228:229], v[50:51], v[66:67]
	v_cndmask_b32_e32 v51, v51, v61, vcc
	v_cndmask_b32_e32 v50, v50, v60, vcc
	v_cndmask_b32_e32 v49, v49, v57, vcc
	v_cndmask_b32_e32 v48, v48, v56, vcc
	v_cndmask_b32_e32 v55, v55, v67, vcc
	v_cndmask_b32_e32 v54, v54, v66, vcc
	v_cndmask_b32_e32 v53, v53, v63, vcc
	v_cndmask_b32_e32 v52, v52, v62, vcc
	v_cvt_pk_bf16_f32 v48, v48, v49
	v_cvt_pk_bf16_f32 v49, v50, v51
	global_store_dwordx2 v[58:59], v[48:49], off offset:256
	v_cvt_pk_bf16_f32 v48, v52, v53
	v_cvt_pk_bf16_f32 v49, v54, v55
	global_store_dwordx2 v[58:59], v[48:49], off offset:288
	v_add_u32_e32 v48, 0x90, v130
	v_ashrrev_i32_e32 v49, 31, v48
	v_lshl_add_u64 v[50:51], v[48:49], 2, s[50:51]
	s_nop 1
	v_lshlrev_b64 v[54:55], 6, v[48:49]
	s_waitcnt vmcnt(38)
	v_mul_f32_e32 v58, 0x3e16c740, v162
	v_lshl_add_u64 v[50:51], s[52:53], 0, v[54:55]
	v_lshl_add_u64 v[54:55], s[82:83], 0, v[54:55]
	v_lshl_add_u64 v[50:51], v[50:51], 0, v[64:65]
	v_lshl_add_u64 v[54:55], v[54:55], 0, v[64:65]
	s_nop 1
	v_pk_mul_f32 v[44:45], v[44:45], v[58:59] op_sel_hi:[1,0]
	s_nop 1
	v_pk_mul_f32 v[46:47], v[46:47], v[58:59] op_sel_hi:[1,0]
	v_pk_mul_f32 v[40:41], v[40:41], v[58:59] op_sel_hi:[1,0]
	v_pk_mul_f32 v[42:43], v[42:43], v[58:59] op_sel_hi:[1,0]
	v_pk_mul_f32 v[36:37], v[36:37], v[58:59] op_sel_hi:[1,0]
	v_pk_mul_f32 v[38:39], v[38:39], v[58:59] op_sel_hi:[1,0]
	v_pk_mul_f32 v[32:33], v[32:33], v[58:59] op_sel_hi:[1,0]
	v_pk_mul_f32 v[34:35], v[34:35], v[58:59] op_sel_hi:[1,0]
	s_waitcnt vmcnt(30)
	v_pk_mul_f32 v[66:67], v[190:191], v[44:45]
	v_pk_mul_f32 v[68:69], v[192:193], v[46:47]
	s_waitcnt vmcnt(22)
	v_pk_mul_f32 v[60:61], v[230:231], v[44:45]
	v_pk_mul_f32 v[62:63], v[232:233], v[46:47]
	v_pk_fma_f32 v[60:61], v[190:191], v[40:41], v[60:61] neg_lo:[0,0,1] neg_hi:[0,0,1]
	v_pk_fma_f32 v[62:63], v[192:193], v[42:43], v[62:63] neg_lo:[0,0,1] neg_hi:[0,0,1]
	v_pk_fma_f32 v[68:69], v[232:233], v[42:43], v[68:69]
	v_pk_fma_f32 v[66:67], v[230:231], v[40:41], v[66:67]
	v_cndmask_b32_e64 v43, v43, v63, s[40:41]
	v_cndmask_b32_e64 v42, v42, v62, s[40:41]
	v_cndmask_b32_e64 v41, v41, v61, s[40:41]
	v_cndmask_b32_e64 v40, v40, v60, s[40:41]
	v_cvt_pk_bf16_f32 v40, v40, v41
	v_cvt_pk_bf16_f32 v41, v42, v43
	v_mad_i64_i32 v[42:43], s[2:3], v48, s33, v[122:123]
	v_lshl_add_u64 v[42:43], v[42:43], 0, s[56:57]
	v_cndmask_b32_e64 v47, v47, v69, s[40:41]
	v_cndmask_b32_e64 v46, v46, v68, s[40:41]
	v_cndmask_b32_e64 v45, v45, v67, s[40:41]
	v_cndmask_b32_e64 v44, v44, v66, s[40:41]
	v_lshl_add_u64 v[42:43], v[42:43], 0, v[124:125]
	global_store_dwordx2 v[42:43], v[40:41], off
	v_cvt_pk_bf16_f32 v40, v44, v45
	v_cvt_pk_bf16_f32 v41, v46, v47
	global_store_dwordx2 v[42:43], v[40:41], off offset:32
	v_pk_mul_f32 v[40:41], v[230:231], v[36:37]
	v_pk_mul_f32 v[44:45], v[232:233], v[38:39]
	v_pk_fma_f32 v[40:41], v[190:191], v[32:33], v[40:41] neg_lo:[0,0,1] neg_hi:[0,0,1]
	v_pk_fma_f32 v[44:45], v[192:193], v[34:35], v[44:45] neg_lo:[0,0,1] neg_hi:[0,0,1]
	v_pk_mul_f32 v[46:47], v[190:191], v[36:37]
	v_pk_mul_f32 v[48:49], v[192:193], v[38:39]
	v_pk_fma_f32 v[46:47], v[230:231], v[32:33], v[46:47]
	v_pk_fma_f32 v[48:49], v[232:233], v[34:35], v[48:49]
	v_cndmask_b32_e32 v35, v35, v45, vcc
	v_cndmask_b32_e32 v34, v34, v44, vcc
	v_cndmask_b32_e32 v33, v33, v41, vcc
	v_cndmask_b32_e32 v32, v32, v40, vcc
	v_cndmask_b32_e32 v39, v39, v49, vcc
	v_cndmask_b32_e32 v38, v38, v48, vcc
	v_cndmask_b32_e32 v37, v37, v47, vcc
	v_cndmask_b32_e32 v36, v36, v46, vcc
	v_cvt_pk_bf16_f32 v32, v32, v33
	v_cvt_pk_bf16_f32 v33, v34, v35
	global_store_dwordx2 v[42:43], v[32:33], off offset:256
	v_cvt_pk_bf16_f32 v32, v36, v37
	v_cvt_pk_bf16_f32 v33, v38, v39
	global_store_dwordx2 v[42:43], v[32:33], off offset:288
	v_add_u32_e32 v32, 0xa0, v130
	v_ashrrev_i32_e32 v33, 31, v32
	v_lshl_add_u64 v[34:35], v[32:33], 2, s[50:51]
	s_nop 1
	v_lshlrev_b64 v[38:39], 6, v[32:33]
	s_waitcnt vmcnt(41)
	v_mul_f32_e32 v42, 0x3e16c740, v164
	v_lshl_add_u64 v[34:35], s[52:53], 0, v[38:39]
	v_lshl_add_u64 v[38:39], s[82:83], 0, v[38:39]
	v_lshl_add_u64 v[34:35], v[34:35], 0, v[64:65]
	v_lshl_add_u64 v[38:39], v[38:39], 0, v[64:65]
	s_nop 1
	v_pk_mul_f32 v[28:29], v[28:29], v[42:43] op_sel_hi:[1,0]
	s_nop 1
	v_pk_mul_f32 v[30:31], v[30:31], v[42:43] op_sel_hi:[1,0]
	v_pk_mul_f32 v[24:25], v[24:25], v[42:43] op_sel_hi:[1,0]
	v_pk_mul_f32 v[26:27], v[26:27], v[42:43] op_sel_hi:[1,0]
	v_pk_mul_f32 v[20:21], v[20:21], v[42:43] op_sel_hi:[1,0]
	v_pk_mul_f32 v[22:23], v[22:23], v[42:43] op_sel_hi:[1,0]
	v_pk_mul_f32 v[16:17], v[16:17], v[42:43] op_sel_hi:[1,0]
	v_pk_mul_f32 v[18:19], v[18:19], v[42:43] op_sel_hi:[1,0]
	s_waitcnt vmcnt(33)
	v_pk_mul_f32 v[48:49], v[194:195], v[28:29]
	v_pk_mul_f32 v[50:51], v[196:197], v[30:31]
	s_waitcnt vmcnt(25)
	v_pk_mul_f32 v[44:45], v[234:235], v[28:29]
	v_pk_mul_f32 v[46:47], v[236:237], v[30:31]
	v_pk_fma_f32 v[44:45], v[194:195], v[24:25], v[44:45] neg_lo:[0,0,1] neg_hi:[0,0,1]
	v_pk_fma_f32 v[46:47], v[196:197], v[26:27], v[46:47] neg_lo:[0,0,1] neg_hi:[0,0,1]
	v_pk_fma_f32 v[50:51], v[236:237], v[26:27], v[50:51]
	v_pk_fma_f32 v[48:49], v[234:235], v[24:25], v[48:49]
	v_cndmask_b32_e64 v27, v27, v47, s[40:41]
	v_cndmask_b32_e64 v26, v26, v46, s[40:41]
	v_cndmask_b32_e64 v25, v25, v45, s[40:41]
	v_cndmask_b32_e64 v24, v24, v44, s[40:41]
	v_cvt_pk_bf16_f32 v24, v24, v25
	v_cvt_pk_bf16_f32 v25, v26, v27
	v_mad_i64_i32 v[26:27], s[2:3], v32, s33, v[122:123]
	v_lshl_add_u64 v[26:27], v[26:27], 0, s[56:57]
	v_cndmask_b32_e64 v31, v31, v51, s[40:41]
	v_cndmask_b32_e64 v30, v30, v50, s[40:41]
	v_cndmask_b32_e64 v29, v29, v49, s[40:41]
	v_cndmask_b32_e64 v28, v28, v48, s[40:41]
	v_lshl_add_u64 v[26:27], v[26:27], 0, v[124:125]
	global_store_dwordx2 v[26:27], v[24:25], off
	v_cvt_pk_bf16_f32 v24, v28, v29
	v_cvt_pk_bf16_f32 v25, v30, v31
	global_store_dwordx2 v[26:27], v[24:25], off offset:32
	v_pk_mul_f32 v[24:25], v[234:235], v[20:21]
	v_pk_mul_f32 v[28:29], v[236:237], v[22:23]
	v_pk_fma_f32 v[24:25], v[194:195], v[16:17], v[24:25] neg_lo:[0,0,1] neg_hi:[0,0,1]
	v_pk_fma_f32 v[28:29], v[196:197], v[18:19], v[28:29] neg_lo:[0,0,1] neg_hi:[0,0,1]
	v_pk_mul_f32 v[30:31], v[194:195], v[20:21]
	v_pk_mul_f32 v[32:33], v[196:197], v[22:23]
	v_pk_fma_f32 v[30:31], v[234:235], v[16:17], v[30:31]
	v_pk_fma_f32 v[32:33], v[236:237], v[18:19], v[32:33]
	v_cndmask_b32_e32 v19, v19, v29, vcc
	v_cndmask_b32_e32 v18, v18, v28, vcc
	v_cndmask_b32_e32 v17, v17, v25, vcc
	v_cndmask_b32_e32 v16, v16, v24, vcc
	v_cndmask_b32_e32 v23, v23, v33, vcc
	v_cndmask_b32_e32 v22, v22, v32, vcc
	v_cndmask_b32_e32 v21, v21, v31, vcc
	v_cndmask_b32_e32 v20, v20, v30, vcc
	v_cvt_pk_bf16_f32 v16, v16, v17
	v_cvt_pk_bf16_f32 v17, v18, v19
	global_store_dwordx2 v[26:27], v[16:17], off offset:256
	v_cvt_pk_bf16_f32 v16, v20, v21
	v_cvt_pk_bf16_f32 v17, v22, v23
	global_store_dwordx2 v[26:27], v[16:17], off offset:288
	v_add_u32_e32 v16, 0xb0, v130
	v_ashrrev_i32_e32 v17, 31, v16
	v_lshl_add_u64 v[18:19], v[16:17], 2, s[50:51]
	s_nop 1
	v_lshlrev_b64 v[22:23], 6, v[16:17]
	s_mov_b32 s51, s17
	s_waitcnt vmcnt(44)
	v_mul_f32_e32 v26, 0x3e16c740, v166
	v_lshl_add_u64 v[18:19], s[52:53], 0, v[22:23]
	v_lshl_add_u64 v[22:23], s[82:83], 0, v[22:23]
	v_lshl_add_u64 v[18:19], v[18:19], 0, v[64:65]
	v_lshl_add_u64 v[22:23], v[22:23], 0, v[64:65]
	s_nop 1
	v_pk_mul_f32 v[12:13], v[12:13], v[26:27] op_sel_hi:[1,0]
	s_nop 1
	v_pk_mul_f32 v[14:15], v[14:15], v[26:27] op_sel_hi:[1,0]
	v_pk_mul_f32 v[8:9], v[8:9], v[26:27] op_sel_hi:[1,0]
	v_pk_mul_f32 v[10:11], v[10:11], v[26:27] op_sel_hi:[1,0]
	v_pk_mul_f32 v[0:1], v[0:1], v[26:27] op_sel_hi:[1,0]
	v_pk_mul_f32 v[2:3], v[2:3], v[26:27] op_sel_hi:[1,0]
	v_pk_mul_f32 v[4:5], v[4:5], v[26:27] op_sel_hi:[1,0]
	v_pk_mul_f32 v[6:7], v[6:7], v[26:27] op_sel_hi:[1,0]
	s_waitcnt vmcnt(36)
	v_pk_mul_f32 v[32:33], v[198:199], v[12:13]
	v_pk_mul_f32 v[34:35], v[200:201], v[14:15]
	s_waitcnt vmcnt(28)
	v_pk_mul_f32 v[28:29], v[238:239], v[12:13]
	v_pk_mul_f32 v[30:31], v[240:241], v[14:15]
	v_pk_fma_f32 v[28:29], v[198:199], v[8:9], v[28:29] neg_lo:[0,0,1] neg_hi:[0,0,1]
	v_pk_fma_f32 v[30:31], v[200:201], v[10:11], v[30:31] neg_lo:[0,0,1] neg_hi:[0,0,1]
	v_pk_fma_f32 v[34:35], v[240:241], v[10:11], v[34:35]
	v_pk_fma_f32 v[32:33], v[238:239], v[8:9], v[32:33]
	v_cndmask_b32_e64 v11, v11, v31, s[40:41]
	v_cndmask_b32_e64 v10, v10, v30, s[40:41]
	v_cndmask_b32_e64 v9, v9, v29, s[40:41]
	v_cndmask_b32_e64 v8, v8, v28, s[40:41]
	v_cvt_pk_bf16_f32 v8, v8, v9
	v_cvt_pk_bf16_f32 v9, v10, v11
	v_mad_i64_i32 v[10:11], s[2:3], v16, s33, v[122:123]
	v_lshl_add_u64 v[10:11], v[10:11], 0, s[56:57]
	v_cndmask_b32_e64 v15, v15, v35, s[40:41]
	v_cndmask_b32_e64 v14, v14, v34, s[40:41]
	v_cndmask_b32_e64 v13, v13, v33, s[40:41]
	v_cndmask_b32_e64 v12, v12, v32, s[40:41]
	v_lshl_add_u64 v[10:11], v[10:11], 0, v[124:125]
	global_store_dwordx2 v[10:11], v[8:9], off
	v_cvt_pk_bf16_f32 v8, v12, v13
	v_cvt_pk_bf16_f32 v9, v14, v15
	global_store_dwordx2 v[10:11], v[8:9], off offset:32
	v_pk_mul_f32 v[8:9], v[238:239], v[0:1]
	v_pk_mul_f32 v[12:13], v[240:241], v[2:3]
	v_pk_fma_f32 v[8:9], v[198:199], v[4:5], v[8:9] neg_lo:[0,0,1] neg_hi:[0,0,1]
	v_pk_fma_f32 v[12:13], v[200:201], v[6:7], v[12:13] neg_lo:[0,0,1] neg_hi:[0,0,1]
	v_pk_mul_f32 v[14:15], v[198:199], v[0:1]
	v_pk_mul_f32 v[16:17], v[200:201], v[2:3]
	v_pk_fma_f32 v[14:15], v[238:239], v[4:5], v[14:15]
	v_pk_fma_f32 v[16:17], v[240:241], v[6:7], v[16:17]
	v_cndmask_b32_e32 v7, v7, v13, vcc
	v_cndmask_b32_e32 v6, v6, v12, vcc
	v_cndmask_b32_e32 v5, v5, v9, vcc
	v_cndmask_b32_e32 v4, v4, v8, vcc
	v_cndmask_b32_e32 v3, v3, v17, vcc
	v_cndmask_b32_e32 v2, v2, v16, vcc
	v_cndmask_b32_e32 v8, v1, v15, vcc
	v_cndmask_b32_e32 v9, v0, v14, vcc
	v_cvt_pk_bf16_f32 v0, v4, v5
	v_cvt_pk_bf16_f32 v1, v6, v7
	global_store_dwordx2 v[10:11], v[0:1], off offset:256
	v_cvt_pk_bf16_f32 v0, v9, v8
	v_cvt_pk_bf16_f32 v1, v2, v3
	s_mov_b64 s[2:3], 0
	global_store_dwordx2 v[10:11], v[0:1], off offset:288
	s_barrier

.LBB0_261:
	v_mov_b32_e32 v64, v203
	s_add_i32 s2, s7, s59
	v_and_b32_e32 v131, 15, v64
	v_or_b32_e32 v132, s2, v131
	v_ashrrev_i32_e32 v133, 31, v132
	v_lshlrev_b64 v[134:135], 2, v[132:133]
	v_lshl_add_u64 v[136:137], s[94:95], 0, v[134:135]
	v_mov_b32_e32 v142, v136
	v_mov_b32_e32 v143, v137
	global_load_dword v136, v[136:137], off
	global_load_dword v144, v[142:143], off offset:64
	global_load_dword v146, v[142:143], off offset:128
	global_load_dword v148, v[142:143], off offset:192
	global_load_dword v150, v[142:143], off offset:512
	global_load_dword v152, v[142:143], off offset:576
	global_load_dword v154, v[142:143], off offset:640
	global_load_dword v156, v[142:143], off offset:704
	v_lshrrev_b32_e32 v64, 2, v64
	s_add_i32 s3, s40, 0xfffffe00
	v_and_or_b32 v64, v64, 12, s3
	v_or_b32_e32 v130, s51, v64
	v_mov_b32_e32 v64, s2
	s_movk_i32 s3, 0xfc3
	v_bitop3_b32 v64, v131, s3, v64 bitop3:0xc8
	v_lshlrev_b32_e32 v64, 1, v64
	v_lshrrev_b64 v[138:139], 3, v[132:133]
	v_lshl_add_u64 v[140:141], s[92:93], 0, v[64:65]
	v_and_b32_e32 v64, 16, v134
	v_and_b32_e32 v139, 0x7ffff, v139
	v_and_b32_e32 v138, 0xfffffe00, v138
	v_lshl_add_u64 v[134:135], v[140:141], 0, v[64:65]
	v_bitop3_b32 v64, v131, 8, s2 bitop3:0xc8
	v_mov_b32_e32 v131, v65
	v_lshl_add_u64 v[140:141], v[138:139], 0, v[130:131]
	v_lshl_add_u64 v[134:135], v[134:135], 0, v[64:65]
	v_lshlrev_b64 v[140:141], 13, v[140:141]
	v_lshl_add_u64 v[140:141], v[134:135], 0, v[140:141]
	s_movk_i32 s11, 0x2000
	s_movk_i32 s3, 0x4000
	s_movk_i32 s10, 0x6000
	s_movk_i32 s2, 0xfd3
	v_readlane_b32 s42, v255, 47
	s_mov_b32 s27, 0x42b17218
	v_readlane_b32 s71, v254, 49
	v_readlane_b32 s84, v255, 49
	v_readlane_b32 s48, v255, 50
	v_readlane_b32 s43, v255, 48
	v_readlane_b32 s87, v255, 51
	s_waitcnt vmcnt(7)
	v_pk_mul_f32 v[126:127], v[126:127], v[136:137] op_sel_hi:[1,0]
	s_nop 0
	v_bfe_u32 v64, v126, 16, 1
	v_add3_u32 v64, v126, v64, s26
	global_store_short_d16_hi v[140:141], v64, off
	v_bfe_u32 v64, v127, 16, 1
	v_add_co_u32_e32 v126, vcc, s11, v140
	v_pk_mul_f32 v[128:129], v[128:129], v[136:137] op_sel_hi:[1,0]
	v_add3_u32 v64, v127, v64, s26
	v_addc_co_u32_e32 v127, vcc, 0, v141, vcc
	global_store_short_d16_hi v[126:127], v64, off
	v_bfe_u32 v64, v128, 16, 1
	v_add_co_u32_e32 v126, vcc, s3, v140
	v_add3_u32 v64, v128, v64, s26
	s_nop 0
	v_addc_co_u32_e32 v127, vcc, 0, v141, vcc
	global_store_short_d16_hi v[126:127], v64, off
	v_bfe_u32 v64, v129, 16, 1
	v_add_co_u32_e32 v126, vcc, s10, v140
	v_add3_u32 v64, v129, v64, s26
	s_nop 0
	v_addc_co_u32_e32 v127, vcc, 0, v141, vcc
	global_store_short_d16_hi v[126:127], v64, off
	v_or_b32_e32 v64, 16, v130
	v_pk_mul_f32 v[122:123], v[122:123], v[136:137] op_sel_hi:[1,0]
	v_lshl_add_u64 v[126:127], v[138:139], 0, v[64:65]
	v_lshlrev_b64 v[126:127], 13, v[126:127]
	v_bfe_u32 v128, v122, 16, 1
	v_lshl_add_u64 v[126:127], v[134:135], 0, v[126:127]
	v_add3_u32 v122, v122, v128, s26
	global_store_short_d16_hi v[126:127], v122, off
	v_bfe_u32 v122, v123, 16, 1
	v_add3_u32 v128, v123, v122, s26
	v_add_co_u32_e32 v122, vcc, s11, v126
	v_pk_mul_f32 v[124:125], v[124:125], v[136:137] op_sel_hi:[1,0]
	s_nop 0
	v_addc_co_u32_e32 v123, vcc, 0, v127, vcc
	global_store_short_d16_hi v[122:123], v128, off
	v_bfe_u32 v122, v124, 16, 1
	v_add3_u32 v124, v124, v122, s26
	v_add_co_u32_e32 v122, vcc, s3, v126
	v_pk_mul_f32 v[118:119], v[118:119], v[136:137] op_sel_hi:[1,0]
	s_nop 0
	v_addc_co_u32_e32 v123, vcc, 0, v127, vcc
	global_store_short_d16_hi v[122:123], v124, off
	v_bfe_u32 v122, v125, 16, 1
	v_add3_u32 v124, v125, v122, s26
	v_add_co_u32_e32 v122, vcc, s10, v126
	v_bfe_u32 v126, v118, 16, 1
	s_nop 0
	v_addc_co_u32_e32 v123, vcc, 0, v127, vcc
	global_store_short_d16_hi v[122:123], v124, off
	v_or_b32_e32 v122, 0x80, v130
	v_mov_b32_e32 v123, v65
	v_lshl_add_u64 v[124:125], v[138:139], 0, v[122:123]
	v_lshlrev_b64 v[124:125], 13, v[124:125]
	v_lshl_add_u64 v[124:125], v[134:135], 0, v[124:125]
	v_add3_u32 v118, v118, v126, s26
	global_store_short_d16_hi v[124:125], v118, off
	v_bfe_u32 v118, v119, 16, 1
	v_add3_u32 v126, v119, v118, s26
	v_add_co_u32_e32 v118, vcc, s11, v124
	v_pk_mul_f32 v[120:121], v[120:121], v[136:137] op_sel_hi:[1,0]
	s_nop 0
	v_addc_co_u32_e32 v119, vcc, 0, v125, vcc
	global_store_short_d16_hi v[118:119], v126, off
	v_bfe_u32 v118, v120, 16, 1
	v_add3_u32 v120, v120, v118, s26
	v_add_co_u32_e32 v118, vcc, s3, v124
	v_pk_mul_f32 v[116:117], v[116:117], v[136:137] op_sel_hi:[1,0]
	s_nop 0
	v_addc_co_u32_e32 v119, vcc, 0, v125, vcc
	global_store_short_d16_hi v[118:119], v120, off
	v_bfe_u32 v118, v121, 16, 1
	v_add3_u32 v120, v121, v118, s26
	v_add_co_u32_e32 v118, vcc, s10, v124
	s_nop 1
	v_addc_co_u32_e32 v119, vcc, 0, v125, vcc
	global_store_short_d16_hi v[118:119], v120, off
	v_pk_mul_f32 v[118:119], v[114:115], v[136:137] op_sel_hi:[1,0]
	v_or_b32_e32 v114, 0x90, v130
	v_mov_b32_e32 v115, v65
	v_lshl_add_u64 v[120:121], v[138:139], 0, v[114:115]
	v_lshlrev_b64 v[120:121], 13, v[120:121]
	v_bfe_u32 v124, v118, 16, 1
	v_lshl_add_u64 v[120:121], v[134:135], 0, v[120:121]
	v_add3_u32 v118, v118, v124, s26
	global_store_short_d16_hi v[120:121], v118, off
	v_bfe_u32 v118, v119, 16, 1
	v_add3_u32 v124, v119, v118, s26
	v_add_co_u32_e32 v118, vcc, s11, v120
	v_mov_b32_e32 v125, v65
	s_nop 0
	v_addc_co_u32_e32 v119, vcc, 0, v121, vcc
	global_store_short_d16_hi v[118:119], v124, off
	v_bfe_u32 v118, v116, 16, 1
	v_add3_u32 v116, v116, v118, s26
	v_add_co_u32_e32 v118, vcc, s3, v120
	s_nop 1
	v_addc_co_u32_e32 v119, vcc, 0, v121, vcc
	global_store_short_d16_hi v[118:119], v116, off
	v_bfe_u32 v116, v117, 16, 1
	v_add3_u32 v118, v117, v116, s26
	v_add_co_u32_e32 v116, vcc, s10, v120
	s_nop 1
	v_addc_co_u32_e32 v117, vcc, 0, v121, vcc
	global_store_short_d16_hi v[116:117], v118, off
	v_or_b32_e32 v116, 16, v132
	v_ashrrev_i32_e32 v117, 31, v116
	v_lshlrev_b64 v[118:119], 2, v[116:117]
	v_lshl_add_u64 v[120:121], s[94:95], 0, v[118:119]
	s_nop 1
	v_bitop3_b32 v119, v132, s2, 16 bitop3:0xc8
	v_lshlrev_b32_e32 v124, 1, v119
	v_lshrrev_b64 v[116:117], 3, v[116:117]
	v_lshl_add_u64 v[124:125], s[92:93], 0, v[124:125]
	v_and_b32_e32 v118, 16, v118
	v_mov_b32_e32 v119, v65
	v_and_b32_e32 v117, 0x7ffff, v117
	v_and_b32_e32 v116, 0xfffffe00, v116
	v_lshl_add_u64 v[118:119], v[124:125], 0, v[118:119]
	v_bitop3_b32 v124, v132, 8, 16 bitop3:0xc8
	v_mov_b32_e32 v125, v65
	v_lshl_add_u64 v[118:119], v[118:119], 0, v[124:125]
	v_lshl_add_u64 v[124:125], v[116:117], 0, v[130:131]
	v_lshlrev_b64 v[124:125], 13, v[124:125]
	v_lshl_add_u64 v[124:125], v[118:119], 0, v[124:125]
	s_movk_i32 s2, 0xfe3
	s_waitcnt vmcnt(22)
	v_pk_mul_f32 v[110:111], v[110:111], v[144:145] op_sel_hi:[1,0]
	v_pk_mul_f32 v[112:113], v[112:113], v[144:145] op_sel_hi:[1,0]
	v_bfe_u32 v121, v110, 16, 1
	v_add3_u32 v110, v110, v121, s26
	global_store_short_d16_hi v[124:125], v110, off
	v_bfe_u32 v110, v111, 16, 1
	v_add3_u32 v121, v111, v110, s26
	v_add_co_u32_e32 v110, vcc, s11, v124
	v_pk_mul_f32 v[102:103], v[102:103], v[144:145] op_sel_hi:[1,0]
	s_nop 0
	v_addc_co_u32_e32 v111, vcc, 0, v125, vcc
	global_store_short_d16_hi v[110:111], v121, off
	v_bfe_u32 v110, v112, 16, 1
	v_add3_u32 v112, v112, v110, s26
	v_add_co_u32_e32 v110, vcc, s3, v124
	v_pk_mul_f32 v[104:105], v[104:105], v[144:145] op_sel_hi:[1,0]
	s_nop 0
	v_addc_co_u32_e32 v111, vcc, 0, v125, vcc
	global_store_short_d16_hi v[110:111], v112, off
	v_bfe_u32 v110, v113, 16, 1
	v_add3_u32 v112, v113, v110, s26
	v_add_co_u32_e32 v110, vcc, s10, v124
	v_pk_mul_f32 v[98:99], v[98:99], v[144:145] op_sel_hi:[1,0]
	s_nop 0
	v_addc_co_u32_e32 v111, vcc, 0, v125, vcc
	global_store_short_d16_hi v[110:111], v112, off
	v_lshl_add_u64 v[110:111], v[116:117], 0, v[64:65]
	v_lshlrev_b64 v[110:111], 13, v[110:111]
	v_bfe_u32 v112, v102, 16, 1
	v_lshl_add_u64 v[110:111], v[118:119], 0, v[110:111]
	v_add3_u32 v102, v102, v112, s26
	global_store_short_d16_hi v[110:111], v102, off
	v_bfe_u32 v102, v103, 16, 1
	v_add3_u32 v112, v103, v102, s26
	v_add_co_u32_e32 v102, vcc, s11, v110
	v_pk_mul_f32 v[100:101], v[100:101], v[144:145] op_sel_hi:[1,0]
	s_nop 0
	v_addc_co_u32_e32 v103, vcc, 0, v111, vcc
	global_store_short_d16_hi v[102:103], v112, off
	v_bfe_u32 v102, v104, 16, 1
	v_add3_u32 v104, v104, v102, s26
	v_add_co_u32_e32 v102, vcc, s3, v110
	s_nop 1
	v_addc_co_u32_e32 v103, vcc, 0, v111, vcc
	global_store_short_d16_hi v[102:103], v104, off
	v_bfe_u32 v102, v105, 16, 1
	v_add3_u32 v104, v105, v102, s26
	v_add_co_u32_e32 v102, vcc, s10, v110
	s_nop 1
	v_addc_co_u32_e32 v103, vcc, 0, v111, vcc
	global_store_short_d16_hi v[102:103], v104, off
	v_pk_mul_f32 v[104:105], v[106:107], v[144:145] op_sel_hi:[1,0]
	v_lshl_add_u64 v[106:107], v[116:117], 0, v[122:123]
	v_pk_mul_f32 v[102:103], v[108:109], v[144:145] op_sel_hi:[1,0]
	v_lshlrev_b64 v[106:107], 13, v[106:107]
	v_bfe_u32 v108, v104, 16, 1
	v_lshl_add_u64 v[106:107], v[118:119], 0, v[106:107]
	v_add3_u32 v104, v104, v108, s26
	global_store_short_d16_hi v[106:107], v104, off
	v_bfe_u32 v104, v105, 16, 1
	v_add3_u32 v108, v105, v104, s26
	v_add_co_u32_e32 v104, vcc, s11, v106
	s_nop 1
	v_addc_co_u32_e32 v105, vcc, 0, v107, vcc
	global_store_short_d16_hi v[104:105], v108, off
	v_bfe_u32 v104, v102, 16, 1
	v_add3_u32 v102, v102, v104, s26
	v_add_co_u32_e32 v104, vcc, s3, v106
	s_nop 1
	v_addc_co_u32_e32 v105, vcc, 0, v107, vcc
	global_store_short_d16_hi v[104:105], v102, off
	v_bfe_u32 v102, v103, 16, 1
	v_add3_u32 v104, v103, v102, s26
	v_add_co_u32_e32 v102, vcc, s10, v106
	v_mov_b32_e32 v105, v65
	s_nop 0
	v_addc_co_u32_e32 v103, vcc, 0, v107, vcc
	global_store_short_d16_hi v[102:103], v104, off
	v_lshl_add_u64 v[102:103], v[116:117], 0, v[114:115]
	v_lshlrev_b64 v[102:103], 13, v[102:103]
	v_bfe_u32 v104, v98, 16, 1
	v_lshl_add_u64 v[102:103], v[118:119], 0, v[102:103]
	v_add3_u32 v98, v98, v104, s26
	global_store_short_d16_hi v[102:103], v98, off
	v_bfe_u32 v98, v99, 16, 1
	v_add3_u32 v104, v99, v98, s26
	v_add_co_u32_e32 v98, vcc, s11, v102
	s_nop 1
	v_addc_co_u32_e32 v99, vcc, 0, v103, vcc
	global_store_short_d16_hi v[98:99], v104, off
	v_bfe_u32 v98, v100, 16, 1
	v_add3_u32 v100, v100, v98, s26
	v_add_co_u32_e32 v98, vcc, s3, v102
	s_nop 1
	v_addc_co_u32_e32 v99, vcc, 0, v103, vcc
	global_store_short_d16_hi v[98:99], v100, off
	v_bfe_u32 v98, v101, 16, 1
	v_add3_u32 v100, v101, v98, s26
	v_add_co_u32_e32 v98, vcc, s10, v102
	s_nop 1
	v_addc_co_u32_e32 v99, vcc, 0, v103, vcc
	global_store_short_d16_hi v[98:99], v100, off
	v_or_b32_e32 v98, 32, v132
	v_ashrrev_i32_e32 v99, 31, v98
	v_lshlrev_b64 v[100:101], 2, v[98:99]
	v_lshl_add_u64 v[102:103], s[94:95], 0, v[100:101]
	s_nop 1
	v_bitop3_b32 v101, v132, s2, 32 bitop3:0xc8
	v_lshlrev_b32_e32 v104, 1, v101
	v_lshrrev_b64 v[98:99], 3, v[98:99]
	v_lshl_add_u64 v[104:105], s[92:93], 0, v[104:105]
	v_and_b32_e32 v100, 16, v100
	v_mov_b32_e32 v101, v65
	v_and_b32_e32 v99, 0x7ffff, v99
	v_and_b32_e32 v98, 0xfffffe00, v98
	v_lshl_add_u64 v[100:101], v[104:105], 0, v[100:101]
	v_bitop3_b32 v104, v132, 8, 32 bitop3:0xc8
	v_mov_b32_e32 v105, v65
	v_lshl_add_u64 v[100:101], v[100:101], 0, v[104:105]
	v_lshl_add_u64 v[104:105], v[98:99], 0, v[130:131]
	v_lshlrev_b64 v[104:105], 13, v[104:105]
	v_lshl_add_u64 v[104:105], v[100:101], 0, v[104:105]
	s_movk_i32 s2, 0xff3
	s_waitcnt vmcnt(37)
	v_pk_mul_f32 v[94:95], v[94:95], v[146:147] op_sel_hi:[1,0]
	v_pk_mul_f32 v[96:97], v[96:97], v[146:147] op_sel_hi:[1,0]
	v_bfe_u32 v103, v94, 16, 1
	v_add3_u32 v94, v94, v103, s26
	global_store_short_d16_hi v[104:105], v94, off
	v_bfe_u32 v94, v95, 16, 1
	v_add3_u32 v103, v95, v94, s26
	v_add_co_u32_e32 v94, vcc, s11, v104
	v_pk_mul_f32 v[86:87], v[86:87], v[146:147] op_sel_hi:[1,0]
	s_nop 0
	v_addc_co_u32_e32 v95, vcc, 0, v105, vcc
	global_store_short_d16_hi v[94:95], v103, off
	v_bfe_u32 v94, v96, 16, 1
	v_add3_u32 v96, v96, v94, s26
	v_add_co_u32_e32 v94, vcc, s3, v104
	v_pk_mul_f32 v[88:89], v[88:89], v[146:147] op_sel_hi:[1,0]
	s_nop 0
	v_addc_co_u32_e32 v95, vcc, 0, v105, vcc
	global_store_short_d16_hi v[94:95], v96, off
	v_bfe_u32 v94, v97, 16, 1
	v_add3_u32 v96, v97, v94, s26
	v_add_co_u32_e32 v94, vcc, s10, v104
	v_pk_mul_f32 v[82:83], v[82:83], v[146:147] op_sel_hi:[1,0]
	s_nop 0
	v_addc_co_u32_e32 v95, vcc, 0, v105, vcc
	global_store_short_d16_hi v[94:95], v96, off
	v_lshl_add_u64 v[94:95], v[98:99], 0, v[64:65]
	v_lshlrev_b64 v[94:95], 13, v[94:95]
	v_bfe_u32 v96, v86, 16, 1
	v_lshl_add_u64 v[94:95], v[100:101], 0, v[94:95]
	v_add3_u32 v86, v86, v96, s26
	global_store_short_d16_hi v[94:95], v86, off
	v_bfe_u32 v86, v87, 16, 1
	v_add3_u32 v96, v87, v86, s26
	v_add_co_u32_e32 v86, vcc, s11, v94
	v_pk_mul_f32 v[84:85], v[84:85], v[146:147] op_sel_hi:[1,0]
	s_nop 0
	v_addc_co_u32_e32 v87, vcc, 0, v95, vcc
	global_store_short_d16_hi v[86:87], v96, off
	v_bfe_u32 v86, v88, 16, 1
	v_add3_u32 v88, v88, v86, s26
	v_add_co_u32_e32 v86, vcc, s3, v94
	s_nop 1
	v_addc_co_u32_e32 v87, vcc, 0, v95, vcc
	global_store_short_d16_hi v[86:87], v88, off
	v_bfe_u32 v86, v89, 16, 1
	v_add3_u32 v88, v89, v86, s26
	v_add_co_u32_e32 v86, vcc, s10, v94
	s_nop 1
	v_addc_co_u32_e32 v87, vcc, 0, v95, vcc
	global_store_short_d16_hi v[86:87], v88, off
	v_pk_mul_f32 v[88:89], v[90:91], v[146:147] op_sel_hi:[1,0]
	v_lshl_add_u64 v[90:91], v[98:99], 0, v[122:123]
	v_pk_mul_f32 v[86:87], v[92:93], v[146:147] op_sel_hi:[1,0]
	v_lshlrev_b64 v[90:91], 13, v[90:91]
	v_bfe_u32 v92, v88, 16, 1
	v_lshl_add_u64 v[90:91], v[100:101], 0, v[90:91]
	v_add3_u32 v88, v88, v92, s26
	global_store_short_d16_hi v[90:91], v88, off
	v_bfe_u32 v88, v89, 16, 1
	v_add3_u32 v92, v89, v88, s26
	v_add_co_u32_e32 v88, vcc, s11, v90
	s_nop 1
	v_addc_co_u32_e32 v89, vcc, 0, v91, vcc
	global_store_short_d16_hi v[88:89], v92, off
	v_bfe_u32 v88, v86, 16, 1
	v_add3_u32 v86, v86, v88, s26
	v_add_co_u32_e32 v88, vcc, s3, v90
	s_nop 1
	v_addc_co_u32_e32 v89, vcc, 0, v91, vcc
	global_store_short_d16_hi v[88:89], v86, off
	v_bfe_u32 v86, v87, 16, 1
	v_add3_u32 v88, v87, v86, s26
	v_add_co_u32_e32 v86, vcc, s10, v90
	v_mov_b32_e32 v89, v65
	s_nop 0
	v_addc_co_u32_e32 v87, vcc, 0, v91, vcc
	global_store_short_d16_hi v[86:87], v88, off
	v_lshl_add_u64 v[86:87], v[98:99], 0, v[114:115]
	v_lshlrev_b64 v[86:87], 13, v[86:87]
	v_bfe_u32 v88, v82, 16, 1
	v_lshl_add_u64 v[86:87], v[100:101], 0, v[86:87]
	v_add3_u32 v82, v82, v88, s26
	global_store_short_d16_hi v[86:87], v82, off
	v_bfe_u32 v82, v83, 16, 1
	v_add3_u32 v88, v83, v82, s26
	v_add_co_u32_e32 v82, vcc, s11, v86
	s_nop 1
	v_addc_co_u32_e32 v83, vcc, 0, v87, vcc
	global_store_short_d16_hi v[82:83], v88, off
	v_bfe_u32 v82, v84, 16, 1
	v_add3_u32 v84, v84, v82, s26
	v_add_co_u32_e32 v82, vcc, s3, v86
	s_nop 1
	v_addc_co_u32_e32 v83, vcc, 0, v87, vcc
	global_store_short_d16_hi v[82:83], v84, off
	v_bfe_u32 v82, v85, 16, 1
	v_add3_u32 v84, v85, v82, s26
	v_add_co_u32_e32 v82, vcc, s10, v86
	s_nop 1
	v_addc_co_u32_e32 v83, vcc, 0, v87, vcc
	global_store_short_d16_hi v[82:83], v84, off
	v_or_b32_e32 v82, 48, v132
	v_ashrrev_i32_e32 v83, 31, v82
	v_lshlrev_b64 v[84:85], 2, v[82:83]
	v_lshl_add_u64 v[86:87], s[94:95], 0, v[84:85]
	s_nop 1
	v_bitop3_b32 v85, v132, s2, 48 bitop3:0xc8
	v_lshlrev_b32_e32 v88, 1, v85
	v_lshrrev_b64 v[82:83], 3, v[82:83]
	v_lshl_add_u64 v[88:89], s[92:93], 0, v[88:89]
	v_and_b32_e32 v84, 16, v84
	v_mov_b32_e32 v85, v65
	v_and_b32_e32 v83, 0x7ffff, v83
	v_and_b32_e32 v82, 0xfffffe00, v82
	v_lshl_add_u64 v[84:85], v[88:89], 0, v[84:85]
	v_bitop3_b32 v88, v132, 8, 48 bitop3:0xc8
	v_mov_b32_e32 v89, v65
	v_lshl_add_u64 v[84:85], v[84:85], 0, v[88:89]
	v_lshl_add_u64 v[88:89], v[82:83], 0, v[130:131]
	v_lshlrev_b64 v[88:89], 13, v[88:89]
	v_lshl_add_u64 v[88:89], v[84:85], 0, v[88:89]
	s_waitcnt vmcnt(52)
	v_pk_mul_f32 v[78:79], v[78:79], v[148:149] op_sel_hi:[1,0]
	v_pk_mul_f32 v[80:81], v[80:81], v[148:149] op_sel_hi:[1,0]
	v_bfe_u32 v87, v78, 16, 1
	v_add3_u32 v78, v78, v87, s26
	global_store_short_d16_hi v[88:89], v78, off
	v_bfe_u32 v78, v79, 16, 1
	v_add3_u32 v87, v79, v78, s26
	v_add_co_u32_e32 v78, vcc, s11, v88
	v_pk_mul_f32 v[70:71], v[70:71], v[148:149] op_sel_hi:[1,0]
	s_nop 0
	v_addc_co_u32_e32 v79, vcc, 0, v89, vcc
	global_store_short_d16_hi v[78:79], v87, off
	v_bfe_u32 v78, v80, 16, 1
	v_add3_u32 v80, v80, v78, s26
	v_add_co_u32_e32 v78, vcc, s3, v88
	v_pk_mul_f32 v[72:73], v[72:73], v[148:149] op_sel_hi:[1,0]
	s_nop 0
	v_addc_co_u32_e32 v79, vcc, 0, v89, vcc
	global_store_short_d16_hi v[78:79], v80, off
	v_bfe_u32 v78, v81, 16, 1
	v_add3_u32 v80, v81, v78, s26
	v_add_co_u32_e32 v78, vcc, s10, v88
	v_pk_mul_f32 v[66:67], v[66:67], v[148:149] op_sel_hi:[1,0]
	s_nop 0
	v_addc_co_u32_e32 v79, vcc, 0, v89, vcc
	global_store_short_d16_hi v[78:79], v80, off
	v_lshl_add_u64 v[78:79], v[82:83], 0, v[64:65]
	v_lshlrev_b64 v[78:79], 13, v[78:79]
	v_bfe_u32 v80, v70, 16, 1
	v_lshl_add_u64 v[78:79], v[84:85], 0, v[78:79]
	v_add3_u32 v70, v70, v80, s26
	global_store_short_d16_hi v[78:79], v70, off
	v_bfe_u32 v70, v71, 16, 1
	v_add3_u32 v80, v71, v70, s26
	v_add_co_u32_e32 v70, vcc, s11, v78
	v_pk_mul_f32 v[68:69], v[68:69], v[148:149] op_sel_hi:[1,0]
	s_nop 0
	v_addc_co_u32_e32 v71, vcc, 0, v79, vcc
	global_store_short_d16_hi v[70:71], v80, off
	v_bfe_u32 v70, v72, 16, 1
	v_add3_u32 v72, v72, v70, s26
	v_add_co_u32_e32 v70, vcc, s3, v78
	s_nop 1
	v_addc_co_u32_e32 v71, vcc, 0, v79, vcc
	global_store_short_d16_hi v[70:71], v72, off
	v_bfe_u32 v70, v73, 16, 1
	v_add3_u32 v72, v73, v70, s26
	v_add_co_u32_e32 v70, vcc, s10, v78
	s_nop 1
	v_addc_co_u32_e32 v71, vcc, 0, v79, vcc
	global_store_short_d16_hi v[70:71], v72, off
	v_pk_mul_f32 v[72:73], v[74:75], v[148:149] op_sel_hi:[1,0]
	v_lshl_add_u64 v[74:75], v[82:83], 0, v[122:123]
	v_pk_mul_f32 v[70:71], v[76:77], v[148:149] op_sel_hi:[1,0]
	v_lshlrev_b64 v[74:75], 13, v[74:75]
	v_bfe_u32 v76, v72, 16, 1
	v_lshl_add_u64 v[74:75], v[84:85], 0, v[74:75]
	v_add3_u32 v72, v72, v76, s26
	global_store_short_d16_hi v[74:75], v72, off
	v_bfe_u32 v72, v73, 16, 1
	v_add3_u32 v76, v73, v72, s26
	v_add_co_u32_e32 v72, vcc, s11, v74
	s_nop 1
	v_addc_co_u32_e32 v73, vcc, 0, v75, vcc
	global_store_short_d16_hi v[72:73], v76, off
	v_bfe_u32 v72, v70, 16, 1
	v_add3_u32 v70, v70, v72, s26
	v_add_co_u32_e32 v72, vcc, s3, v74
	s_nop 1
	v_addc_co_u32_e32 v73, vcc, 0, v75, vcc
	global_store_short_d16_hi v[72:73], v70, off
	v_bfe_u32 v70, v71, 16, 1
	v_add3_u32 v72, v71, v70, s26
	v_add_co_u32_e32 v70, vcc, s10, v74
	s_nop 1
	v_addc_co_u32_e32 v71, vcc, 0, v75, vcc
	global_store_short_d16_hi v[70:71], v72, off
	v_lshl_add_u64 v[70:71], v[82:83], 0, v[114:115]
	v_lshlrev_b64 v[70:71], 13, v[70:71]
	v_bfe_u32 v72, v66, 16, 1
	v_lshl_add_u64 v[70:71], v[84:85], 0, v[70:71]
	v_add3_u32 v66, v66, v72, s26
	global_store_short_d16_hi v[70:71], v66, off
	v_bfe_u32 v66, v67, 16, 1
	v_add3_u32 v72, v67, v66, s26
	v_add_co_u32_e32 v66, vcc, s11, v70
	v_mov_b32_e32 v75, v65
	s_nop 0
	v_addc_co_u32_e32 v67, vcc, 0, v71, vcc
	global_store_short_d16_hi v[66:67], v72, off
	v_bfe_u32 v66, v68, 16, 1
	v_add3_u32 v68, v68, v66, s26
	v_add_co_u32_e32 v66, vcc, s3, v70
	s_nop 1
	v_addc_co_u32_e32 v67, vcc, 0, v71, vcc
	global_store_short_d16_hi v[66:67], v68, off
	v_bfe_u32 v66, v69, 16, 1
	v_add3_u32 v68, v69, v66, s26
	v_add_co_u32_e32 v66, vcc, s10, v70
	s_nop 1
	v_addc_co_u32_e32 v67, vcc, 0, v71, vcc
	global_store_short_d16_hi v[66:67], v68, off
	v_add_u32_e32 v66, 0x80, v132
	v_ashrrev_i32_e32 v67, 31, v66
	v_lshlrev_b64 v[68:69], 2, v[66:67]
	v_lshl_add_u64 v[70:71], s[94:95], 0, v[68:69]
	s_nop 1
	v_and_b32_e32 v69, 0xfc3, v66
	v_lshlrev_b32_e32 v74, 1, v69
	v_lshrrev_b64 v[72:73], 3, v[66:67]
	v_lshl_add_u64 v[74:75], s[92:93], 0, v[74:75]
	v_and_b32_e32 v68, 16, v68
	v_mov_b32_e32 v69, v65
	v_and_b32_e32 v73, 0x7ffff, v73
	v_and_b32_e32 v72, 0xfffffe00, v72
	v_lshl_add_u64 v[68:69], v[74:75], 0, v[68:69]
	v_and_b32_e32 v66, 8, v66
	v_mov_b32_e32 v67, v65
	v_lshl_add_u64 v[66:67], v[68:69], 0, v[66:67]
	v_lshl_add_u64 v[68:69], v[72:73], 0, v[130:131]
	v_lshlrev_b64 v[68:69], 13, v[68:69]
	v_lshl_add_u64 v[68:69], v[66:67], 0, v[68:69]
	s_waitcnt vmcnt(63)
	v_pk_mul_f32 v[60:61], v[60:61], v[150:151] op_sel_hi:[1,0]
	v_pk_mul_f32 v[62:63], v[62:63], v[150:151] op_sel_hi:[1,0]
	v_bfe_u32 v71, v60, 16, 1
	v_add3_u32 v60, v60, v71, s26
	global_store_short_d16_hi v[68:69], v60, off
	v_bfe_u32 v60, v61, 16, 1
	v_add3_u32 v71, v61, v60, s26
	v_add_co_u32_e32 v60, vcc, s11, v68
	v_pk_mul_f32 v[56:57], v[56:57], v[150:151] op_sel_hi:[1,0]
	s_nop 0
	v_addc_co_u32_e32 v61, vcc, 0, v69, vcc
	global_store_short_d16_hi v[60:61], v71, off
	v_bfe_u32 v60, v62, 16, 1
	v_add3_u32 v62, v62, v60, s26
	v_add_co_u32_e32 v60, vcc, s3, v68
	v_pk_mul_f32 v[58:59], v[58:59], v[150:151] op_sel_hi:[1,0]
	s_nop 0
	v_addc_co_u32_e32 v61, vcc, 0, v69, vcc
	global_store_short_d16_hi v[60:61], v62, off
	v_bfe_u32 v60, v63, 16, 1
	v_add3_u32 v62, v63, v60, s26
	v_add_co_u32_e32 v60, vcc, s10, v68
	v_pk_mul_f32 v[52:53], v[52:53], v[150:151] op_sel_hi:[1,0]
	s_nop 0
	v_addc_co_u32_e32 v61, vcc, 0, v69, vcc
	global_store_short_d16_hi v[60:61], v62, off
	v_lshl_add_u64 v[60:61], v[72:73], 0, v[64:65]
	v_lshlrev_b64 v[60:61], 13, v[60:61]
	v_bfe_u32 v62, v56, 16, 1
	v_lshl_add_u64 v[60:61], v[66:67], 0, v[60:61]
	v_add3_u32 v56, v56, v62, s26
	global_store_short_d16_hi v[60:61], v56, off
	v_bfe_u32 v56, v57, 16, 1
	v_add3_u32 v62, v57, v56, s26
	v_add_co_u32_e32 v56, vcc, s11, v60
	v_pk_mul_f32 v[54:55], v[54:55], v[150:151] op_sel_hi:[1,0]
	s_nop 0
	v_addc_co_u32_e32 v57, vcc, 0, v61, vcc
	global_store_short_d16_hi v[56:57], v62, off
	v_bfe_u32 v56, v58, 16, 1
	v_add3_u32 v58, v58, v56, s26
	v_add_co_u32_e32 v56, vcc, s3, v60
	v_pk_mul_f32 v[48:49], v[48:49], v[150:151] op_sel_hi:[1,0]
	s_nop 0
	v_addc_co_u32_e32 v57, vcc, 0, v61, vcc
	global_store_short_d16_hi v[56:57], v58, off
	v_bfe_u32 v56, v59, 16, 1
	v_add3_u32 v58, v59, v56, s26
	v_add_co_u32_e32 v56, vcc, s10, v60
	v_pk_mul_f32 v[50:51], v[50:51], v[150:151] op_sel_hi:[1,0]
	s_nop 0
	v_addc_co_u32_e32 v57, vcc, 0, v61, vcc
	global_store_short_d16_hi v[56:57], v58, off
	v_lshl_add_u64 v[56:57], v[72:73], 0, v[122:123]
	v_lshlrev_b64 v[56:57], 13, v[56:57]
	v_bfe_u32 v58, v52, 16, 1
	v_lshl_add_u64 v[56:57], v[66:67], 0, v[56:57]
	v_add3_u32 v52, v52, v58, s26
	global_store_short_d16_hi v[56:57], v52, off
	v_bfe_u32 v52, v53, 16, 1
	v_add3_u32 v58, v53, v52, s26
	v_add_co_u32_e32 v52, vcc, s11, v56
	s_nop 1
	v_addc_co_u32_e32 v53, vcc, 0, v57, vcc
	global_store_short_d16_hi v[52:53], v58, off
	v_bfe_u32 v52, v54, 16, 1
	v_add3_u32 v54, v54, v52, s26
	v_add_co_u32_e32 v52, vcc, s3, v56
	s_nop 1
	v_addc_co_u32_e32 v53, vcc, 0, v57, vcc
	global_store_short_d16_hi v[52:53], v54, off
	v_bfe_u32 v52, v55, 16, 1
	v_add3_u32 v54, v55, v52, s26
	v_add_co_u32_e32 v52, vcc, s10, v56
	s_nop 1
	v_addc_co_u32_e32 v53, vcc, 0, v57, vcc
	global_store_short_d16_hi v[52:53], v54, off
	v_lshl_add_u64 v[52:53], v[72:73], 0, v[114:115]
	v_lshlrev_b64 v[52:53], 13, v[52:53]
	v_bfe_u32 v54, v48, 16, 1
	v_lshl_add_u64 v[52:53], v[66:67], 0, v[52:53]
	v_add3_u32 v48, v48, v54, s26
	global_store_short_d16_hi v[52:53], v48, off
	v_bfe_u32 v48, v49, 16, 1
	v_add3_u32 v54, v49, v48, s26
	v_add_co_u32_e32 v48, vcc, s11, v52
	v_mov_b32_e32 v57, v65
	s_nop 0
	v_addc_co_u32_e32 v49, vcc, 0, v53, vcc
	global_store_short_d16_hi v[48:49], v54, off
	v_bfe_u32 v48, v50, 16, 1
	v_add3_u32 v50, v50, v48, s26
	v_add_co_u32_e32 v48, vcc, s3, v52
	s_nop 1
	v_addc_co_u32_e32 v49, vcc, 0, v53, vcc
	global_store_short_d16_hi v[48:49], v50, off
	v_bfe_u32 v48, v51, 16, 1
	v_add3_u32 v50, v51, v48, s26
	v_add_co_u32_e32 v48, vcc, s10, v52
	s_nop 1
	v_addc_co_u32_e32 v49, vcc, 0, v53, vcc
	global_store_short_d16_hi v[48:49], v50, off
	v_add_u32_e32 v48, 0x90, v132
	v_ashrrev_i32_e32 v49, 31, v48
	v_lshlrev_b64 v[50:51], 2, v[48:49]
	v_lshl_add_u64 v[52:53], s[94:95], 0, v[50:51]
	s_nop 1
	v_and_b32_e32 v51, 0xfd3, v48
	v_lshlrev_b32_e32 v56, 1, v51
	v_lshrrev_b64 v[54:55], 3, v[48:49]
	v_lshl_add_u64 v[56:57], s[92:93], 0, v[56:57]
	v_and_b32_e32 v50, 16, v50
	v_mov_b32_e32 v51, v65
	v_and_b32_e32 v55, 0x7ffff, v55
	v_and_b32_e32 v54, 0xfffffe00, v54
	v_lshl_add_u64 v[50:51], v[56:57], 0, v[50:51]
	v_and_b32_e32 v48, 8, v48
	v_mov_b32_e32 v49, v65
	v_lshl_add_u64 v[48:49], v[50:51], 0, v[48:49]
	v_lshl_add_u64 v[50:51], v[54:55], 0, v[130:131]
	v_lshlrev_b64 v[50:51], 13, v[50:51]
	v_lshl_add_u64 v[50:51], v[48:49], 0, v[50:51]
	s_waitcnt vmcnt(63)
	v_pk_mul_f32 v[44:45], v[44:45], v[152:153] op_sel_hi:[1,0]
	v_pk_mul_f32 v[46:47], v[46:47], v[152:153] op_sel_hi:[1,0]
	v_bfe_u32 v53, v44, 16, 1
	v_add3_u32 v44, v44, v53, s26
	global_store_short_d16_hi v[50:51], v44, off
	v_bfe_u32 v44, v45, 16, 1
	v_add3_u32 v53, v45, v44, s26
	v_add_co_u32_e32 v44, vcc, s11, v50
	v_pk_mul_f32 v[40:41], v[40:41], v[152:153] op_sel_hi:[1,0]
	s_nop 0
	v_addc_co_u32_e32 v45, vcc, 0, v51, vcc
	global_store_short_d16_hi v[44:45], v53, off
	v_bfe_u32 v44, v46, 16, 1
	v_add3_u32 v46, v46, v44, s26
	v_add_co_u32_e32 v44, vcc, s3, v50
	v_pk_mul_f32 v[42:43], v[42:43], v[152:153] op_sel_hi:[1,0]
	s_nop 0
	v_addc_co_u32_e32 v45, vcc, 0, v51, vcc
	global_store_short_d16_hi v[44:45], v46, off
	v_bfe_u32 v44, v47, 16, 1
	v_add3_u32 v46, v47, v44, s26
	v_add_co_u32_e32 v44, vcc, s10, v50
	v_pk_mul_f32 v[36:37], v[36:37], v[152:153] op_sel_hi:[1,0]
	s_nop 0
	v_addc_co_u32_e32 v45, vcc, 0, v51, vcc
	global_store_short_d16_hi v[44:45], v46, off
	v_lshl_add_u64 v[44:45], v[54:55], 0, v[64:65]
	v_lshlrev_b64 v[44:45], 13, v[44:45]
	v_bfe_u32 v46, v40, 16, 1
	v_lshl_add_u64 v[44:45], v[48:49], 0, v[44:45]
	v_add3_u32 v40, v40, v46, s26
	global_store_short_d16_hi v[44:45], v40, off
	v_bfe_u32 v40, v41, 16, 1
	v_add3_u32 v46, v41, v40, s26
	v_add_co_u32_e32 v40, vcc, s11, v44
	v_pk_mul_f32 v[38:39], v[38:39], v[152:153] op_sel_hi:[1,0]
	s_nop 0
	v_addc_co_u32_e32 v41, vcc, 0, v45, vcc
	global_store_short_d16_hi v[40:41], v46, off
	v_bfe_u32 v40, v42, 16, 1
	v_add3_u32 v42, v42, v40, s26
	v_add_co_u32_e32 v40, vcc, s3, v44
	v_pk_mul_f32 v[32:33], v[32:33], v[152:153] op_sel_hi:[1,0]
	s_nop 0
	v_addc_co_u32_e32 v41, vcc, 0, v45, vcc
	global_store_short_d16_hi v[40:41], v42, off
	v_bfe_u32 v40, v43, 16, 1
	v_add3_u32 v42, v43, v40, s26
	v_add_co_u32_e32 v40, vcc, s10, v44
	v_pk_mul_f32 v[34:35], v[34:35], v[152:153] op_sel_hi:[1,0]
	s_nop 0
	v_addc_co_u32_e32 v41, vcc, 0, v45, vcc
	global_store_short_d16_hi v[40:41], v42, off
	v_lshl_add_u64 v[40:41], v[54:55], 0, v[122:123]
	v_lshlrev_b64 v[40:41], 13, v[40:41]
	v_bfe_u32 v42, v36, 16, 1
	v_lshl_add_u64 v[40:41], v[48:49], 0, v[40:41]
	v_add3_u32 v36, v36, v42, s26
	global_store_short_d16_hi v[40:41], v36, off
	v_bfe_u32 v36, v37, 16, 1
	v_add3_u32 v42, v37, v36, s26
	v_add_co_u32_e32 v36, vcc, s11, v40
	s_nop 1
	v_addc_co_u32_e32 v37, vcc, 0, v41, vcc
	global_store_short_d16_hi v[36:37], v42, off
	v_bfe_u32 v36, v38, 16, 1
	v_add3_u32 v38, v38, v36, s26
	v_add_co_u32_e32 v36, vcc, s3, v40
	s_nop 1
	v_addc_co_u32_e32 v37, vcc, 0, v41, vcc
	global_store_short_d16_hi v[36:37], v38, off
	v_bfe_u32 v36, v39, 16, 1
	v_add3_u32 v38, v39, v36, s26
	v_add_co_u32_e32 v36, vcc, s10, v40
	s_nop 1
	v_addc_co_u32_e32 v37, vcc, 0, v41, vcc
	global_store_short_d16_hi v[36:37], v38, off
	v_lshl_add_u64 v[36:37], v[54:55], 0, v[114:115]
	v_lshlrev_b64 v[36:37], 13, v[36:37]
	v_bfe_u32 v38, v32, 16, 1
	v_lshl_add_u64 v[36:37], v[48:49], 0, v[36:37]
	v_add3_u32 v32, v32, v38, s26
	global_store_short_d16_hi v[36:37], v32, off
	v_bfe_u32 v32, v33, 16, 1
	v_add3_u32 v38, v33, v32, s26
	v_add_co_u32_e32 v32, vcc, s11, v36
	v_mov_b32_e32 v41, v65
	s_nop 0
	v_addc_co_u32_e32 v33, vcc, 0, v37, vcc
	global_store_short_d16_hi v[32:33], v38, off
	v_bfe_u32 v32, v34, 16, 1
	v_add3_u32 v34, v34, v32, s26
	v_add_co_u32_e32 v32, vcc, s3, v36
	s_nop 1
	v_addc_co_u32_e32 v33, vcc, 0, v37, vcc
	global_store_short_d16_hi v[32:33], v34, off
	v_bfe_u32 v32, v35, 16, 1
	v_add3_u32 v34, v35, v32, s26
	v_add_co_u32_e32 v32, vcc, s10, v36
	s_nop 1
	v_addc_co_u32_e32 v33, vcc, 0, v37, vcc
	global_store_short_d16_hi v[32:33], v34, off
	v_add_u32_e32 v32, 0xa0, v132
	v_ashrrev_i32_e32 v33, 31, v32
	v_lshlrev_b64 v[34:35], 2, v[32:33]
	v_lshl_add_u64 v[36:37], s[94:95], 0, v[34:35]
	s_nop 1
	v_and_b32_e32 v35, 0xfe3, v32
	v_lshlrev_b32_e32 v40, 1, v35
	v_lshrrev_b64 v[38:39], 3, v[32:33]
	v_lshl_add_u64 v[40:41], s[92:93], 0, v[40:41]
	v_and_b32_e32 v34, 16, v34
	v_mov_b32_e32 v35, v65
	v_and_b32_e32 v39, 0x7ffff, v39
	v_and_b32_e32 v38, 0xfffffe00, v38
	v_lshl_add_u64 v[34:35], v[40:41], 0, v[34:35]
	v_and_b32_e32 v32, 8, v32
	v_mov_b32_e32 v33, v65
	v_lshl_add_u64 v[32:33], v[34:35], 0, v[32:33]
	v_lshl_add_u64 v[34:35], v[38:39], 0, v[130:131]
	v_lshlrev_b64 v[34:35], 13, v[34:35]
	v_lshl_add_u64 v[34:35], v[32:33], 0, v[34:35]
	s_waitcnt vmcnt(63)
	v_pk_mul_f32 v[28:29], v[28:29], v[154:155] op_sel_hi:[1,0]
	v_pk_mul_f32 v[30:31], v[30:31], v[154:155] op_sel_hi:[1,0]
	v_bfe_u32 v37, v28, 16, 1
	v_add3_u32 v28, v28, v37, s26
	global_store_short_d16_hi v[34:35], v28, off
	v_bfe_u32 v28, v29, 16, 1
	v_add3_u32 v37, v29, v28, s26
	v_add_co_u32_e32 v28, vcc, s11, v34
	v_pk_mul_f32 v[24:25], v[24:25], v[154:155] op_sel_hi:[1,0]
	s_nop 0
	v_addc_co_u32_e32 v29, vcc, 0, v35, vcc
	global_store_short_d16_hi v[28:29], v37, off
	v_bfe_u32 v28, v30, 16, 1
	v_add3_u32 v30, v30, v28, s26
	v_add_co_u32_e32 v28, vcc, s3, v34
	v_pk_mul_f32 v[26:27], v[26:27], v[154:155] op_sel_hi:[1,0]
	s_nop 0
	v_addc_co_u32_e32 v29, vcc, 0, v35, vcc
	global_store_short_d16_hi v[28:29], v30, off
	v_bfe_u32 v28, v31, 16, 1
	v_add3_u32 v30, v31, v28, s26
	v_add_co_u32_e32 v28, vcc, s10, v34
	v_pk_mul_f32 v[20:21], v[20:21], v[154:155] op_sel_hi:[1,0]
	s_nop 0
	v_addc_co_u32_e32 v29, vcc, 0, v35, vcc
	global_store_short_d16_hi v[28:29], v30, off
	v_lshl_add_u64 v[28:29], v[38:39], 0, v[64:65]
	v_lshlrev_b64 v[28:29], 13, v[28:29]
	v_bfe_u32 v30, v24, 16, 1
	v_lshl_add_u64 v[28:29], v[32:33], 0, v[28:29]
	v_add3_u32 v24, v24, v30, s26
	global_store_short_d16_hi v[28:29], v24, off
	v_bfe_u32 v24, v25, 16, 1
	v_add3_u32 v30, v25, v24, s26
	v_add_co_u32_e32 v24, vcc, s11, v28
	v_pk_mul_f32 v[22:23], v[22:23], v[154:155] op_sel_hi:[1,0]
	s_nop 0
	v_addc_co_u32_e32 v25, vcc, 0, v29, vcc
	global_store_short_d16_hi v[24:25], v30, off
	v_bfe_u32 v24, v26, 16, 1
	v_add3_u32 v26, v26, v24, s26
	v_add_co_u32_e32 v24, vcc, s3, v28
	v_pk_mul_f32 v[16:17], v[16:17], v[154:155] op_sel_hi:[1,0]
	s_nop 0
	v_addc_co_u32_e32 v25, vcc, 0, v29, vcc
	global_store_short_d16_hi v[24:25], v26, off
	v_bfe_u32 v24, v27, 16, 1
	v_add3_u32 v26, v27, v24, s26
	v_add_co_u32_e32 v24, vcc, s10, v28
	v_pk_mul_f32 v[18:19], v[18:19], v[154:155] op_sel_hi:[1,0]
	s_nop 0
	v_addc_co_u32_e32 v25, vcc, 0, v29, vcc
	global_store_short_d16_hi v[24:25], v26, off
	v_lshl_add_u64 v[24:25], v[38:39], 0, v[122:123]
	v_lshlrev_b64 v[24:25], 13, v[24:25]
	v_bfe_u32 v26, v20, 16, 1
	v_lshl_add_u64 v[24:25], v[32:33], 0, v[24:25]
	v_add3_u32 v20, v20, v26, s26
	global_store_short_d16_hi v[24:25], v20, off
	v_bfe_u32 v20, v21, 16, 1
	v_add3_u32 v26, v21, v20, s26
	v_add_co_u32_e32 v20, vcc, s11, v24
	s_nop 1
	v_addc_co_u32_e32 v21, vcc, 0, v25, vcc
	global_store_short_d16_hi v[20:21], v26, off
	v_bfe_u32 v20, v22, 16, 1
	v_add3_u32 v22, v22, v20, s26
	v_add_co_u32_e32 v20, vcc, s3, v24
	s_nop 1
	v_addc_co_u32_e32 v21, vcc, 0, v25, vcc
	global_store_short_d16_hi v[20:21], v22, off
	v_bfe_u32 v20, v23, 16, 1
	v_add3_u32 v22, v23, v20, s26
	v_add_co_u32_e32 v20, vcc, s10, v24
	s_nop 1
	v_addc_co_u32_e32 v21, vcc, 0, v25, vcc
	global_store_short_d16_hi v[20:21], v22, off
	v_lshl_add_u64 v[20:21], v[38:39], 0, v[114:115]
	v_lshlrev_b64 v[20:21], 13, v[20:21]
	v_bfe_u32 v22, v16, 16, 1
	v_lshl_add_u64 v[20:21], v[32:33], 0, v[20:21]
	v_add3_u32 v16, v16, v22, s26
	global_store_short_d16_hi v[20:21], v16, off
	v_bfe_u32 v16, v17, 16, 1
	v_add3_u32 v22, v17, v16, s26
	v_add_co_u32_e32 v16, vcc, s11, v20
	v_mov_b32_e32 v25, v65
	s_nop 0
	v_addc_co_u32_e32 v17, vcc, 0, v21, vcc
	global_store_short_d16_hi v[16:17], v22, off
	v_bfe_u32 v16, v18, 16, 1
	v_add3_u32 v18, v18, v16, s26
	v_add_co_u32_e32 v16, vcc, s3, v20
	s_nop 1
	v_addc_co_u32_e32 v17, vcc, 0, v21, vcc
	global_store_short_d16_hi v[16:17], v18, off
	v_bfe_u32 v16, v19, 16, 1
	v_add3_u32 v18, v19, v16, s26
	v_add_co_u32_e32 v16, vcc, s10, v20
	s_nop 1
	v_addc_co_u32_e32 v17, vcc, 0, v21, vcc
	global_store_short_d16_hi v[16:17], v18, off
	v_add_u32_e32 v16, 0xb0, v132
	v_ashrrev_i32_e32 v17, 31, v16
	v_lshlrev_b64 v[20:21], 2, v[16:17]
	v_lshl_add_u64 v[18:19], s[94:95], 0, v[20:21]
	s_nop 1
	v_and_b32_e32 v19, 0xff3, v16
	v_lshlrev_b32_e32 v24, 1, v19
	v_lshrrev_b64 v[22:23], 3, v[16:17]
	v_lshl_add_u64 v[24:25], s[92:93], 0, v[24:25]
	v_and_b32_e32 v20, 16, v20
	v_mov_b32_e32 v21, v65
	v_and_b32_e32 v23, 0x7ffff, v23
	v_and_b32_e32 v22, 0xfffffe00, v22
	v_lshl_add_u64 v[20:21], v[24:25], 0, v[20:21]
	v_and_b32_e32 v16, 8, v16
	v_mov_b32_e32 v17, v65
	v_lshl_add_u64 v[16:17], v[20:21], 0, v[16:17]
	v_lshl_add_u64 v[20:21], v[22:23], 0, v[130:131]
	v_lshlrev_b64 v[20:21], 13, v[20:21]
	v_lshl_add_u64 v[20:21], v[16:17], 0, v[20:21]
	s_waitcnt vmcnt(63)
	v_pk_mul_f32 v[12:13], v[12:13], v[156:157] op_sel_hi:[1,0]
	v_pk_mul_f32 v[14:15], v[14:15], v[156:157] op_sel_hi:[1,0]
	v_bfe_u32 v19, v12, 16, 1
	v_add3_u32 v12, v12, v19, s26
	global_store_short_d16_hi v[20:21], v12, off
	v_bfe_u32 v12, v13, 16, 1
	v_add3_u32 v19, v13, v12, s26
	v_add_co_u32_e32 v12, vcc, s11, v20
	v_pk_mul_f32 v[8:9], v[8:9], v[156:157] op_sel_hi:[1,0]
	s_nop 0
	v_addc_co_u32_e32 v13, vcc, 0, v21, vcc
	global_store_short_d16_hi v[12:13], v19, off
	v_bfe_u32 v12, v14, 16, 1
	v_add3_u32 v14, v14, v12, s26
	v_add_co_u32_e32 v12, vcc, s3, v20
	v_pk_mul_f32 v[10:11], v[10:11], v[156:157] op_sel_hi:[1,0]
	s_nop 0
	v_addc_co_u32_e32 v13, vcc, 0, v21, vcc
	global_store_short_d16_hi v[12:13], v14, off
	v_bfe_u32 v12, v15, 16, 1
	v_add3_u32 v14, v15, v12, s26
	v_add_co_u32_e32 v12, vcc, s10, v20
	v_pk_mul_f32 v[4:5], v[4:5], v[156:157] op_sel_hi:[1,0]
	s_nop 0
	v_addc_co_u32_e32 v13, vcc, 0, v21, vcc
	global_store_short_d16_hi v[12:13], v14, off
	v_lshl_add_u64 v[12:13], v[22:23], 0, v[64:65]
	v_lshlrev_b64 v[12:13], 13, v[12:13]
	v_bfe_u32 v14, v8, 16, 1
	v_lshl_add_u64 v[12:13], v[16:17], 0, v[12:13]
	v_add3_u32 v8, v8, v14, s26
	global_store_short_d16_hi v[12:13], v8, off
	v_bfe_u32 v8, v9, 16, 1
	v_add3_u32 v14, v9, v8, s26
	v_add_co_u32_e32 v8, vcc, s11, v12
	v_pk_mul_f32 v[6:7], v[6:7], v[156:157] op_sel_hi:[1,0]
	s_nop 0
	v_addc_co_u32_e32 v9, vcc, 0, v13, vcc
	global_store_short_d16_hi v[8:9], v14, off
	v_bfe_u32 v8, v10, 16, 1
	v_add3_u32 v10, v10, v8, s26
	v_add_co_u32_e32 v8, vcc, s3, v12
	v_pk_mul_f32 v[0:1], v[0:1], v[156:157] op_sel_hi:[1,0]
	s_nop 0
	v_addc_co_u32_e32 v9, vcc, 0, v13, vcc
	global_store_short_d16_hi v[8:9], v10, off
	v_bfe_u32 v8, v11, 16, 1
	v_add3_u32 v10, v11, v8, s26
	v_add_co_u32_e32 v8, vcc, s10, v12
	v_pk_mul_f32 v[2:3], v[2:3], v[156:157] op_sel_hi:[1,0]
	s_nop 0
	v_addc_co_u32_e32 v9, vcc, 0, v13, vcc
	global_store_short_d16_hi v[8:9], v10, off
	v_lshl_add_u64 v[8:9], v[22:23], 0, v[122:123]
	v_lshlrev_b64 v[8:9], 13, v[8:9]
	v_bfe_u32 v10, v4, 16, 1
	v_lshl_add_u64 v[8:9], v[16:17], 0, v[8:9]
	v_add3_u32 v4, v4, v10, s26
	global_store_short_d16_hi v[8:9], v4, off
	v_bfe_u32 v4, v5, 16, 1
	v_add3_u32 v10, v5, v4, s26
	v_add_co_u32_e32 v4, vcc, s11, v8
	s_nop 1
	v_addc_co_u32_e32 v5, vcc, 0, v9, vcc
	global_store_short_d16_hi v[4:5], v10, off
	v_bfe_u32 v4, v6, 16, 1
	v_add3_u32 v6, v6, v4, s26
	v_add_co_u32_e32 v4, vcc, s3, v8
	s_mov_b64 s[2:3], 0
	s_nop 0
	v_addc_co_u32_e32 v5, vcc, 0, v9, vcc
	global_store_short_d16_hi v[4:5], v6, off
	v_bfe_u32 v4, v7, 16, 1
	v_add3_u32 v6, v7, v4, s26
	v_add_co_u32_e32 v4, vcc, s10, v8
	s_nop 1
	v_addc_co_u32_e32 v5, vcc, 0, v9, vcc
	global_store_short_d16_hi v[4:5], v6, off
	v_lshl_add_u64 v[4:5], v[22:23], 0, v[114:115]
	v_lshlrev_b64 v[4:5], 13, v[4:5]
	v_bfe_u32 v6, v0, 16, 1
	v_lshl_add_u64 v[4:5], v[16:17], 0, v[4:5]
	v_add3_u32 v0, v0, v6, s26
	global_store_short_d16_hi v[4:5], v0, off
	v_bfe_u32 v0, v1, 16, 1
	v_add3_u32 v6, v1, v0, s26
	v_add_co_u32_e32 v0, vcc, 0x2000, v4
	s_nop 1
	v_addc_co_u32_e32 v1, vcc, 0, v5, vcc
	global_store_short_d16_hi v[0:1], v6, off
	v_bfe_u32 v0, v2, 16, 1
	v_add3_u32 v2, v2, v0, s26
	v_add_co_u32_e32 v0, vcc, 0x4000, v4
	s_nop 1
	v_addc_co_u32_e32 v1, vcc, 0, v5, vcc
	global_store_short_d16_hi v[0:1], v2, off
	v_bfe_u32 v0, v3, 16, 1
	v_add3_u32 v2, v3, v0, s26
	v_add_co_u32_e32 v0, vcc, 0x6000, v4
	s_nop 1
	v_addc_co_u32_e32 v1, vcc, 0, v5, vcc
	global_store_short_d16_hi v[0:1], v2, off
	s_barrier

.LBB0_267:
	v_mov_b32_e32 v64, v203
	s_add_i32 s7, s7, s59
	v_readlane_b32 s0, v255, 43
	v_and_or_b32 v130, v64, 15, s7
	v_ashrrev_i32_e32 v131, 31, v130
	v_lshl_add_u64 v[132:133], v[130:131], 2, s[94:95]
	v_mov_b32_e32 v136, v132
	v_mov_b32_e32 v137, v133
	global_load_dword v132, v[132:133], off
	global_load_dword v138, v[136:137], off offset:64
	global_load_dword v140, v[136:137], off offset:128
	global_load_dword v142, v[136:137], off offset:192
	global_load_dword v144, v[136:137], off offset:512
	global_load_dword v146, v[136:137], off offset:576
	global_load_dword v148, v[136:137], off offset:640
	global_load_dword v150, v[136:137], off offset:704
	v_readlane_b32 s1, v255, 44
	s_or_b32 s2, s51, s40
	v_lshrrev_b32_e32 v64, 1, v64
	v_readlane_b32 s42, v255, 47
	s_mov_b32 s27, 0x42b17218
	v_readlane_b32 s71, v254, 49
	v_readlane_b32 s43, v255, 48
	s_mov_b32 s87, s77
	s_mov_b32 s77, s80
	s_waitcnt vmcnt(7)
	v_pk_mul_f32 v[122:123], v[122:123], v[132:133] op_sel_hi:[1,0]
	v_pk_mul_f32 v[134:135], v[124:125], v[132:133] op_sel_hi:[1,0]
	v_pk_mul_f32 v[128:129], v[128:129], v[132:133] op_sel_hi:[1,0]
	v_pk_mul_f32 v[126:127], v[126:127], v[132:133] op_sel_hi:[1,0]
	v_cvt_pk_bf16_f32 v124, v122, v123
	v_mov_b64_e32 v[122:123], s[0:1]
	v_cvt_pk_bf16_f32 v126, v126, v127
	v_cvt_pk_bf16_f32 v127, v128, v129
	v_mad_i64_i32 v[128:129], s[0:1], v130, s33, v[122:123]
	s_ashr_i32 s0, s2, 6
	s_mulk_i32 s0, 0x60
	s_ashr_i32 s1, s0, 31
	v_readlane_b32 s2, v255, 45
	s_lshl_b64 s[0:1], s[0:1], 1
	v_lshl_add_u64 v[128:129], v[128:129], 0, s[0:1]
	v_and_or_b32 v64, v64, 24, s2
	v_lshlrev_b32_e32 v64, 1, v64
	v_pk_mul_f32 v[116:117], v[116:117], v[132:133] op_sel_hi:[1,0]
	v_pk_mul_f32 v[114:115], v[114:115], v[132:133] op_sel_hi:[1,0]
	v_pk_mul_f32 v[120:121], v[120:121], v[132:133] op_sel_hi:[1,0]
	v_pk_mul_f32 v[118:119], v[118:119], v[132:133] op_sel_hi:[1,0]
	v_lshl_add_u64 v[128:129], v[128:129], 0, v[64:65]
	v_cvt_pk_bf16_f32 v114, v114, v115
	v_cvt_pk_bf16_f32 v115, v116, v117
	v_cvt_pk_bf16_f32 v116, v118, v119
	v_cvt_pk_bf16_f32 v117, v120, v121
	global_store_dwordx4 v[128:129], v[114:117], off offset:384
	v_cvt_pk_bf16_f32 v125, v134, v135
	global_store_dwordx4 v[128:129], v[124:127], off
	v_or_b32_e32 v114, 16, v130
	v_ashrrev_i32_e32 v115, 31, v114
	v_lshl_add_u64 v[116:117], v[114:115], 2, s[94:95]
	s_nop 1
	s_waitcnt vmcnt(8)
	v_pk_mul_f32 v[100:101], v[100:101], v[138:139] op_sel_hi:[1,0]
	v_pk_mul_f32 v[98:99], v[98:99], v[138:139] op_sel_hi:[1,0]
	v_pk_mul_f32 v[102:103], v[102:103], v[138:139] op_sel_hi:[1,0]
	v_cvt_pk_bf16_f32 v98, v98, v99
	v_cvt_pk_bf16_f32 v99, v100, v101
	v_cvt_pk_bf16_f32 v100, v102, v103
	v_mad_i64_i32 v[102:103], s[2:3], v114, s33, v[122:123]
	v_pk_mul_f32 v[104:105], v[104:105], v[138:139] op_sel_hi:[1,0]
	v_lshl_add_u64 v[102:103], v[102:103], 0, s[0:1]
	v_cvt_pk_bf16_f32 v101, v104, v105
	v_lshl_add_u64 v[102:103], v[102:103], 0, v[64:65]
	global_store_dwordx4 v[102:103], v[98:101], off
	v_pk_mul_f32 v[104:105], v[112:113], v[138:139] op_sel_hi:[1,0]
	s_nop 0
	v_pk_mul_f32 v[100:101], v[108:109], v[138:139] op_sel_hi:[1,0]
	v_pk_mul_f32 v[98:99], v[106:107], v[138:139] op_sel_hi:[1,0]
	v_pk_mul_f32 v[106:107], v[110:111], v[138:139] op_sel_hi:[1,0]
	v_cvt_pk_bf16_f32 v98, v98, v99
	v_cvt_pk_bf16_f32 v99, v100, v101
	v_cvt_pk_bf16_f32 v100, v106, v107
	v_cvt_pk_bf16_f32 v101, v104, v105
	global_store_dwordx4 v[102:103], v[98:101], off offset:384
	s_nop 1
	v_or_b32_e32 v98, 32, v130
	v_ashrrev_i32_e32 v99, 31, v98
	v_lshl_add_u64 v[100:101], v[98:99], 2, s[94:95]
	s_nop 1
	s_waitcnt vmcnt(9)
	v_pk_mul_f32 v[84:85], v[84:85], v[140:141] op_sel_hi:[1,0]
	v_pk_mul_f32 v[82:83], v[82:83], v[140:141] op_sel_hi:[1,0]
	v_pk_mul_f32 v[86:87], v[86:87], v[140:141] op_sel_hi:[1,0]
	v_cvt_pk_bf16_f32 v82, v82, v83
	v_cvt_pk_bf16_f32 v83, v84, v85
	v_cvt_pk_bf16_f32 v84, v86, v87
	v_mad_i64_i32 v[86:87], s[2:3], v98, s33, v[122:123]
	v_pk_mul_f32 v[88:89], v[88:89], v[140:141] op_sel_hi:[1,0]
	v_lshl_add_u64 v[86:87], v[86:87], 0, s[0:1]
	v_cvt_pk_bf16_f32 v85, v88, v89
	v_lshl_add_u64 v[86:87], v[86:87], 0, v[64:65]
	global_store_dwordx4 v[86:87], v[82:85], off
	v_pk_mul_f32 v[88:89], v[96:97], v[140:141] op_sel_hi:[1,0]
	s_nop 0
	v_pk_mul_f32 v[84:85], v[92:93], v[140:141] op_sel_hi:[1,0]
	v_pk_mul_f32 v[82:83], v[90:91], v[140:141] op_sel_hi:[1,0]
	v_pk_mul_f32 v[90:91], v[94:95], v[140:141] op_sel_hi:[1,0]
	v_cvt_pk_bf16_f32 v82, v82, v83
	v_cvt_pk_bf16_f32 v83, v84, v85
	v_cvt_pk_bf16_f32 v84, v90, v91
	v_cvt_pk_bf16_f32 v85, v88, v89
	global_store_dwordx4 v[86:87], v[82:85], off offset:384
	s_nop 1
	v_or_b32_e32 v82, 48, v130
	v_ashrrev_i32_e32 v83, 31, v82
	v_lshl_add_u64 v[84:85], v[82:83], 2, s[94:95]
	s_nop 1
	s_waitcnt vmcnt(10)
	v_pk_mul_f32 v[68:69], v[68:69], v[142:143] op_sel_hi:[1,0]
	v_pk_mul_f32 v[66:67], v[66:67], v[142:143] op_sel_hi:[1,0]
	v_pk_mul_f32 v[70:71], v[70:71], v[142:143] op_sel_hi:[1,0]
	v_cvt_pk_bf16_f32 v66, v66, v67
	v_cvt_pk_bf16_f32 v67, v68, v69
	v_cvt_pk_bf16_f32 v68, v70, v71
	v_mad_i64_i32 v[70:71], s[2:3], v82, s33, v[122:123]
	v_pk_mul_f32 v[72:73], v[72:73], v[142:143] op_sel_hi:[1,0]
	v_lshl_add_u64 v[70:71], v[70:71], 0, s[0:1]
	v_cvt_pk_bf16_f32 v69, v72, v73
	v_lshl_add_u64 v[70:71], v[70:71], 0, v[64:65]
	global_store_dwordx4 v[70:71], v[66:69], off
	v_pk_mul_f32 v[72:73], v[80:81], v[142:143] op_sel_hi:[1,0]
	s_nop 0
	v_pk_mul_f32 v[68:69], v[76:77], v[142:143] op_sel_hi:[1,0]
	v_pk_mul_f32 v[66:67], v[74:75], v[142:143] op_sel_hi:[1,0]
	v_pk_mul_f32 v[74:75], v[78:79], v[142:143] op_sel_hi:[1,0]
	v_cvt_pk_bf16_f32 v66, v66, v67
	v_cvt_pk_bf16_f32 v67, v68, v69
	v_cvt_pk_bf16_f32 v68, v74, v75
	v_cvt_pk_bf16_f32 v69, v72, v73
	global_store_dwordx4 v[70:71], v[66:69], off offset:384
	s_nop 1
	v_add_u32_e32 v66, 0x80, v130
	v_ashrrev_i32_e32 v67, 31, v66
	v_lshl_add_u64 v[68:69], v[66:67], 2, s[94:95]
	s_nop 1
	s_waitcnt vmcnt(11)
	v_pk_mul_f32 v[50:51], v[50:51], v[144:145] op_sel_hi:[1,0]
	v_pk_mul_f32 v[48:49], v[48:49], v[144:145] op_sel_hi:[1,0]
	v_pk_mul_f32 v[52:53], v[52:53], v[144:145] op_sel_hi:[1,0]
	v_cvt_pk_bf16_f32 v48, v48, v49
	v_cvt_pk_bf16_f32 v49, v50, v51
	v_cvt_pk_bf16_f32 v50, v52, v53
	v_mad_i64_i32 v[52:53], s[2:3], v66, s33, v[122:123]
	v_pk_mul_f32 v[54:55], v[54:55], v[144:145] op_sel_hi:[1,0]
	v_lshl_add_u64 v[52:53], v[52:53], 0, s[0:1]
	v_cvt_pk_bf16_f32 v51, v54, v55
	v_lshl_add_u64 v[52:53], v[52:53], 0, v[64:65]
	global_store_dwordx4 v[52:53], v[48:51], off
	v_pk_mul_f32 v[54:55], v[62:63], v[144:145] op_sel_hi:[1,0]
	s_nop 0
	v_pk_mul_f32 v[50:51], v[58:59], v[144:145] op_sel_hi:[1,0]
	v_pk_mul_f32 v[48:49], v[56:57], v[144:145] op_sel_hi:[1,0]
	v_pk_mul_f32 v[56:57], v[60:61], v[144:145] op_sel_hi:[1,0]
	v_cvt_pk_bf16_f32 v48, v48, v49
	v_cvt_pk_bf16_f32 v49, v50, v51
	v_cvt_pk_bf16_f32 v50, v56, v57
	v_cvt_pk_bf16_f32 v51, v54, v55
	global_store_dwordx4 v[52:53], v[48:51], off offset:384
	s_nop 1
	v_add_u32_e32 v48, 0x90, v130
	v_ashrrev_i32_e32 v49, 31, v48
	v_lshl_add_u64 v[50:51], v[48:49], 2, s[94:95]
	s_nop 1
	s_waitcnt vmcnt(12)
	v_pk_mul_f32 v[34:35], v[34:35], v[146:147] op_sel_hi:[1,0]
	v_pk_mul_f32 v[32:33], v[32:33], v[146:147] op_sel_hi:[1,0]
	v_pk_mul_f32 v[36:37], v[36:37], v[146:147] op_sel_hi:[1,0]
	v_cvt_pk_bf16_f32 v32, v32, v33
	v_cvt_pk_bf16_f32 v33, v34, v35
	v_cvt_pk_bf16_f32 v34, v36, v37
	v_mad_i64_i32 v[36:37], s[2:3], v48, s33, v[122:123]
	v_pk_mul_f32 v[38:39], v[38:39], v[146:147] op_sel_hi:[1,0]
	v_lshl_add_u64 v[36:37], v[36:37], 0, s[0:1]
	v_cvt_pk_bf16_f32 v35, v38, v39
	v_lshl_add_u64 v[36:37], v[36:37], 0, v[64:65]
	global_store_dwordx4 v[36:37], v[32:35], off
	v_pk_mul_f32 v[38:39], v[46:47], v[146:147] op_sel_hi:[1,0]
	s_nop 0
	v_pk_mul_f32 v[34:35], v[42:43], v[146:147] op_sel_hi:[1,0]
	v_pk_mul_f32 v[32:33], v[40:41], v[146:147] op_sel_hi:[1,0]
	v_pk_mul_f32 v[40:41], v[44:45], v[146:147] op_sel_hi:[1,0]
	v_cvt_pk_bf16_f32 v32, v32, v33
	v_cvt_pk_bf16_f32 v33, v34, v35
	v_cvt_pk_bf16_f32 v34, v40, v41
	v_cvt_pk_bf16_f32 v35, v38, v39
	global_store_dwordx4 v[36:37], v[32:35], off offset:384
	s_nop 1
	v_add_u32_e32 v32, 0xa0, v130
	v_ashrrev_i32_e32 v33, 31, v32
	v_lshl_add_u64 v[34:35], v[32:33], 2, s[94:95]
	s_nop 1
	s_waitcnt vmcnt(13)
	v_pk_mul_f32 v[18:19], v[18:19], v[148:149] op_sel_hi:[1,0]
	v_pk_mul_f32 v[16:17], v[16:17], v[148:149] op_sel_hi:[1,0]
	v_pk_mul_f32 v[20:21], v[20:21], v[148:149] op_sel_hi:[1,0]
	v_cvt_pk_bf16_f32 v16, v16, v17
	v_cvt_pk_bf16_f32 v17, v18, v19
	v_cvt_pk_bf16_f32 v18, v20, v21
	v_mad_i64_i32 v[20:21], s[2:3], v32, s33, v[122:123]
	v_pk_mul_f32 v[22:23], v[22:23], v[148:149] op_sel_hi:[1,0]
	v_lshl_add_u64 v[20:21], v[20:21], 0, s[0:1]
	v_cvt_pk_bf16_f32 v19, v22, v23
	v_lshl_add_u64 v[20:21], v[20:21], 0, v[64:65]
	global_store_dwordx4 v[20:21], v[16:19], off
	v_pk_mul_f32 v[22:23], v[30:31], v[148:149] op_sel_hi:[1,0]
	s_nop 0
	v_pk_mul_f32 v[18:19], v[26:27], v[148:149] op_sel_hi:[1,0]
	v_pk_mul_f32 v[16:17], v[24:25], v[148:149] op_sel_hi:[1,0]
	v_pk_mul_f32 v[24:25], v[28:29], v[148:149] op_sel_hi:[1,0]
	v_cvt_pk_bf16_f32 v16, v16, v17
	v_cvt_pk_bf16_f32 v17, v18, v19
	v_cvt_pk_bf16_f32 v18, v24, v25
	v_cvt_pk_bf16_f32 v19, v22, v23
	global_store_dwordx4 v[20:21], v[16:19], off offset:384
	s_nop 1
	v_add_u32_e32 v16, 0xb0, v130
	v_ashrrev_i32_e32 v17, 31, v16
	v_lshl_add_u64 v[18:19], v[16:17], 2, s[94:95]
	s_nop 1
	s_waitcnt vmcnt(14)
	v_pk_mul_f32 v[10:11], v[10:11], v[150:151] op_sel_hi:[1,0]
	v_pk_mul_f32 v[8:9], v[8:9], v[150:151] op_sel_hi:[1,0]
	v_pk_mul_f32 v[12:13], v[12:13], v[150:151] op_sel_hi:[1,0]
	v_cvt_pk_bf16_f32 v8, v8, v9
	v_cvt_pk_bf16_f32 v9, v10, v11
	v_cvt_pk_bf16_f32 v10, v12, v13
	v_mad_i64_i32 v[12:13], s[2:3], v16, s33, v[122:123]
	v_pk_mul_f32 v[14:15], v[14:15], v[150:151] op_sel_hi:[1,0]
	v_lshl_add_u64 v[12:13], v[12:13], 0, s[0:1]
	v_cvt_pk_bf16_f32 v11, v14, v15
	v_lshl_add_u64 v[12:13], v[12:13], 0, v[64:65]
	global_store_dwordx4 v[12:13], v[8:11], off
	v_pk_mul_f32 v[6:7], v[6:7], v[150:151] op_sel_hi:[1,0]
	v_pk_mul_f32 v[4:5], v[4:5], v[150:151] op_sel_hi:[1,0]
	v_pk_mul_f32 v[8:9], v[2:3], v[150:151] op_sel_hi:[1,0]
	v_pk_mul_f32 v[2:3], v[0:1], v[150:151] op_sel_hi:[1,0]
	v_cvt_pk_bf16_f32 v0, v4, v5
	v_cvt_pk_bf16_f32 v1, v6, v7
	v_cvt_pk_bf16_f32 v2, v2, v3
	v_cvt_pk_bf16_f32 v3, v8, v9
	global_store_dwordx4 v[12:13], v[0:3], off offset:384
	s_barrier
